# full stack + GEMM compute segments: redundant post-barrier lgkmcnt(0) and mid-block setprio pair removed
# speedup vs baseline: 1.0059x; 1.0023x over previous
.LBB0_115:
	ds_read_b128 v[148:151], v154
	ds_read_b128 v[158:161], v154 offset:1024
	ds_read_b128 v[162:165], v154 offset:2048
	ds_read_b128 v[166:169], v154 offset:3072
	ds_read_b128 v[170:173], v155
	ds_read_b128 v[174:177], v155 offset:1024
	ds_read_b128 v[178:181], v155 offset:2048
	ds_read_b128 v[182:185], v155 offset:3072
	s_add_u32 s46, s44, 0xfff00080
	s_addc_u32 s47, s45, -1
	s_cmp_eq_u32 s69, 60
	s_cselect_b32 s49, s35, s47
	s_cselect_b32 s48, s43, s46
	s_cselect_b32 s47, s37, s68
	s_cselect_b32 s46, s66, s67
	v_lshl_add_u64 v[218:219], s[44:45], 0, v[140:141]
	s_add_i32 m0, s54, 0xc000
	ds_read_b128 v[186:189], v156
	ds_read_b128 v[190:193], v156 offset:1024
	ds_read_b128 v[194:197], v156 offset:2048
	ds_read_b128 v[198:201], v156 offset:3072
	ds_read_b128 v[202:205], v156 offset:4096
	ds_read_b128 v[206:209], v156 offset:5120
	ds_read_b128 v[210:213], v156 offset:6144
	ds_read_b128 v[214:217], v156 offset:7168
	global_load_lds_dwordx4 v[218:219], off
	v_lshl_add_u64 v[218:219], s[44:45], 0, v[142:143]
	s_add_i32 m0, s54, 0xe000
	s_nop 0
	global_load_lds_dwordx4 v[218:219], off
	s_waitcnt vmcnt(8)
	s_waitcnt lgkmcnt(0)
	s_barrier
	s_setprio 1
	v_mfma_f32_16x16x32_bf16 v[126:129], v[148:151], v[186:189], v[126:129]
	v_mfma_f32_16x16x32_bf16 v[122:125], v[162:165], v[186:189], v[122:125]
	v_mfma_f32_16x16x32_bf16 v[118:121], v[148:151], v[194:197], v[118:121]
	v_mfma_f32_16x16x32_bf16 v[110:113], v[162:165], v[194:197], v[110:113]
	v_mfma_f32_16x16x32_bf16 v[102:105], v[148:151], v[202:205], v[102:105]
	v_mfma_f32_16x16x32_bf16 v[94:97], v[162:165], v[202:205], v[94:97]
	v_mfma_f32_16x16x32_bf16 v[86:89], v[148:151], v[210:213], v[86:89]
	v_mfma_f32_16x16x32_bf16 v[78:81], v[162:165], v[210:213], v[78:81]
	v_mfma_f32_16x16x32_bf16 v[126:129], v[158:161], v[190:193], v[126:129]
	v_mfma_f32_16x16x32_bf16 v[122:125], v[166:169], v[190:193], v[122:125]
	v_mfma_f32_16x16x32_bf16 v[118:121], v[158:161], v[198:201], v[118:121]
	v_mfma_f32_16x16x32_bf16 v[110:113], v[166:169], v[198:201], v[110:113]
	v_mfma_f32_16x16x32_bf16 v[102:105], v[158:161], v[206:209], v[102:105]
	v_mfma_f32_16x16x32_bf16 v[94:97], v[166:169], v[206:209], v[94:97]
	v_mfma_f32_16x16x32_bf16 v[86:89], v[158:161], v[214:217], v[86:89]
	v_mfma_f32_16x16x32_bf16 v[78:81], v[166:169], v[214:217], v[78:81]
	v_mfma_f32_16x16x32_bf16 v[114:117], v[170:173], v[186:189], v[114:117]
	v_mfma_f32_16x16x32_bf16 v[106:109], v[178:181], v[186:189], v[106:109]
	v_mfma_f32_16x16x32_bf16 v[98:101], v[170:173], v[194:197], v[98:101]
	v_mfma_f32_16x16x32_bf16 v[90:93], v[178:181], v[194:197], v[90:93]
	v_mfma_f32_16x16x32_bf16 v[82:85], v[170:173], v[202:205], v[82:85]
	v_mfma_f32_16x16x32_bf16 v[74:77], v[178:181], v[202:205], v[74:77]
	v_mfma_f32_16x16x32_bf16 v[70:73], v[170:173], v[210:213], v[70:73]
	v_mfma_f32_16x16x32_bf16 v[66:69], v[178:181], v[210:213], v[66:69]
	v_mfma_f32_16x16x32_bf16 v[114:117], v[174:177], v[190:193], v[114:117]
	v_mfma_f32_16x16x32_bf16 v[106:109], v[182:185], v[190:193], v[106:109]
	v_mfma_f32_16x16x32_bf16 v[98:101], v[174:177], v[198:201], v[98:101]
	v_mfma_f32_16x16x32_bf16 v[90:93], v[182:185], v[198:201], v[90:93]
	s_setprio 3
	s_barrier
	v_mfma_f32_16x16x32_bf16 v[82:85], v[174:177], v[206:209], v[82:85]
	v_mfma_f32_16x16x32_bf16 v[74:77], v[182:185], v[206:209], v[74:77]
	v_mfma_f32_16x16x32_bf16 v[70:73], v[174:177], v[214:217], v[70:73]
	v_mfma_f32_16x16x32_bf16 v[66:69], v[182:185], v[214:217], v[66:69]
	s_setprio 0
	s_add_i32 s70, s64, s51
	v_lshl_add_u64 v[218:219], s[46:47], 0, v[134:135]
	s_mov_b32 m0, s70
	ds_read_b128 v[186:189], v156 offset:16384
	ds_read_b128 v[190:193], v156 offset:17408
	ds_read_b128 v[194:197], v156 offset:18432
	ds_read_b128 v[198:201], v156 offset:19456
	ds_read_b128 v[202:205], v156 offset:20480
	ds_read_b128 v[206:209], v156 offset:21504
	ds_read_b128 v[210:213], v156 offset:22528
	ds_read_b128 v[214:217], v156 offset:23552
	global_load_lds_dwordx4 v[218:219], off
	s_add_i32 m0, s70, 0x2000
	s_add_u32 s70, s46, 0x100000
	v_lshl_add_u64 v[220:221], s[46:47], 0, v[130:131]
	s_addc_u32 s71, s47, 0
	s_add_i32 s72, s65, s51
	global_load_lds_dwordx4 v[220:221], off
	v_lshl_add_u64 v[222:223], s[70:71], 0, v[134:135]
	s_mov_b32 m0, s72
	v_lshl_add_u64 v[224:225], s[48:49], 0, v[132:133]
	global_load_lds_dwordx4 v[222:223], off
	v_lshl_add_u64 v[222:223], s[70:71], 0, v[130:131]
	s_add_i32 m0, s72, 0x2000
	s_nop 0
	global_load_lds_dwordx4 v[222:223], off
	v_lshl_add_u64 v[222:223], s[48:49], 0, v[136:137]
	s_mov_b32 m0, s54
	s_nop 0
	global_load_lds_dwordx4 v[222:223], off
	s_mov_b32 m0, s55
	s_nop 0
	global_load_lds_dwordx4 v[224:225], off
	s_waitcnt vmcnt(8)
	s_waitcnt lgkmcnt(0)
	s_barrier
	s_setprio 1
	v_mfma_f32_16x16x32_bf16 v[62:65], v[148:151], v[186:189], v[62:65]
	v_mfma_f32_16x16x32_bf16 v[58:61], v[162:165], v[186:189], v[58:61]
	v_mfma_f32_16x16x32_bf16 v[54:57], v[148:151], v[194:197], v[54:57]
	v_mfma_f32_16x16x32_bf16 v[46:49], v[162:165], v[194:197], v[46:49]
	v_mfma_f32_16x16x32_bf16 v[38:41], v[148:151], v[202:205], v[38:41]
	v_mfma_f32_16x16x32_bf16 v[30:33], v[162:165], v[202:205], v[30:33]
	v_mfma_f32_16x16x32_bf16 v[22:25], v[148:151], v[210:213], v[22:25]
	v_mfma_f32_16x16x32_bf16 v[14:17], v[162:165], v[210:213], v[14:17]
	v_mfma_f32_16x16x32_bf16 v[62:65], v[158:161], v[190:193], v[62:65]
	v_mfma_f32_16x16x32_bf16 v[58:61], v[166:169], v[190:193], v[58:61]
	v_mfma_f32_16x16x32_bf16 v[54:57], v[158:161], v[198:201], v[54:57]
	v_mfma_f32_16x16x32_bf16 v[46:49], v[166:169], v[198:201], v[46:49]
	v_mfma_f32_16x16x32_bf16 v[38:41], v[158:161], v[206:209], v[38:41]
	v_mfma_f32_16x16x32_bf16 v[30:33], v[166:169], v[206:209], v[30:33]
	v_mfma_f32_16x16x32_bf16 v[22:25], v[158:161], v[214:217], v[22:25]
	v_mfma_f32_16x16x32_bf16 v[14:17], v[166:169], v[214:217], v[14:17]
	v_mfma_f32_16x16x32_bf16 v[50:53], v[170:173], v[186:189], v[50:53]
	v_mfma_f32_16x16x32_bf16 v[42:45], v[178:181], v[186:189], v[42:45]
	v_mfma_f32_16x16x32_bf16 v[34:37], v[170:173], v[194:197], v[34:37]
	v_mfma_f32_16x16x32_bf16 v[26:29], v[178:181], v[194:197], v[26:29]
	v_mfma_f32_16x16x32_bf16 v[18:21], v[170:173], v[202:205], v[18:21]
	v_mfma_f32_16x16x32_bf16 v[10:13], v[178:181], v[202:205], v[10:13]
	v_mfma_f32_16x16x32_bf16 v[6:9], v[170:173], v[210:213], v[6:9]
	v_mfma_f32_16x16x32_bf16 v[2:5], v[178:181], v[210:213], v[2:5]
	v_mfma_f32_16x16x32_bf16 v[50:53], v[174:177], v[190:193], v[50:53]
	v_mfma_f32_16x16x32_bf16 v[42:45], v[182:185], v[190:193], v[42:45]
	v_mfma_f32_16x16x32_bf16 v[34:37], v[174:177], v[198:201], v[34:37]
	v_mfma_f32_16x16x32_bf16 v[26:29], v[182:185], v[198:201], v[26:29]
	s_setprio 3
	s_barrier
	v_mfma_f32_16x16x32_bf16 v[18:21], v[174:177], v[206:209], v[18:21]
	v_mfma_f32_16x16x32_bf16 v[10:13], v[182:185], v[206:209], v[10:13]
	v_mfma_f32_16x16x32_bf16 v[6:9], v[174:177], v[214:217], v[6:9]
	v_mfma_f32_16x16x32_bf16 v[2:5], v[182:185], v[214:217], v[2:5]
	s_setprio 0
	s_add_i32 s70, 0, 0x18000
	v_add_u32_e32 v138, s70, v152
	s_add_i32 s71, 0, 0x1c000
	ds_read_b128 v[148:151], v138
	ds_read_b128 v[158:161], v138 offset:1024
	ds_read_b128 v[162:165], v138 offset:2048
	ds_read_b128 v[166:169], v138 offset:3072
	v_add_u32_e32 v138, s71, v152
	ds_read_b128 v[170:173], v138
	ds_read_b128 v[174:177], v138 offset:1024
	ds_read_b128 v[178:181], v138 offset:2048
	ds_read_b128 v[182:185], v138 offset:3072
	s_add_u32 s48, s48, 0x100000
	s_addc_u32 s49, s49, 0
	s_mov_b32 m0, s56
	v_lshl_add_u64 v[226:227], s[48:49], 0, v[136:137]
	ds_read_b128 v[186:189], v156 offset:32768
	ds_read_b128 v[190:193], v156 offset:33792
	ds_read_b128 v[194:197], v156 offset:34816
	ds_read_b128 v[198:201], v156 offset:35840
	ds_read_b128 v[202:205], v156 offset:36864
	ds_read_b128 v[206:209], v156 offset:37888
	ds_read_b128 v[210:213], v156 offset:38912
	ds_read_b128 v[214:217], v156 offset:39936
	global_load_lds_dwordx4 v[226:227], off
	v_lshl_add_u64 v[226:227], s[48:49], 0, v[132:133]
	s_mov_b32 m0, s57
	s_nop 0
	global_load_lds_dwordx4 v[226:227], off
	s_waitcnt vmcnt(8)
	s_waitcnt lgkmcnt(0)
	s_barrier
	s_setprio 1
	v_mfma_f32_16x16x32_bf16 v[126:129], v[148:151], v[186:189], v[126:129]
	v_mfma_f32_16x16x32_bf16 v[122:125], v[162:165], v[186:189], v[122:125]
	v_mfma_f32_16x16x32_bf16 v[118:121], v[148:151], v[194:197], v[118:121]
	v_mfma_f32_16x16x32_bf16 v[110:113], v[162:165], v[194:197], v[110:113]
	v_mfma_f32_16x16x32_bf16 v[102:105], v[148:151], v[202:205], v[102:105]
	v_mfma_f32_16x16x32_bf16 v[94:97], v[162:165], v[202:205], v[94:97]
	v_mfma_f32_16x16x32_bf16 v[86:89], v[148:151], v[210:213], v[86:89]
	v_mfma_f32_16x16x32_bf16 v[78:81], v[162:165], v[210:213], v[78:81]
	v_mfma_f32_16x16x32_bf16 v[126:129], v[158:161], v[190:193], v[126:129]
	v_mfma_f32_16x16x32_bf16 v[122:125], v[166:169], v[190:193], v[122:125]
	v_mfma_f32_16x16x32_bf16 v[118:121], v[158:161], v[198:201], v[118:121]
	v_mfma_f32_16x16x32_bf16 v[110:113], v[166:169], v[198:201], v[110:113]
	v_mfma_f32_16x16x32_bf16 v[102:105], v[158:161], v[206:209], v[102:105]
	v_mfma_f32_16x16x32_bf16 v[94:97], v[166:169], v[206:209], v[94:97]
	v_mfma_f32_16x16x32_bf16 v[86:89], v[158:161], v[214:217], v[86:89]
	v_mfma_f32_16x16x32_bf16 v[78:81], v[166:169], v[214:217], v[78:81]
	v_mfma_f32_16x16x32_bf16 v[114:117], v[170:173], v[186:189], v[114:117]
	v_mfma_f32_16x16x32_bf16 v[106:109], v[178:181], v[186:189], v[106:109]
	v_mfma_f32_16x16x32_bf16 v[98:101], v[170:173], v[194:197], v[98:101]
	v_mfma_f32_16x16x32_bf16 v[90:93], v[178:181], v[194:197], v[90:93]
	v_mfma_f32_16x16x32_bf16 v[82:85], v[170:173], v[202:205], v[82:85]
	v_mfma_f32_16x16x32_bf16 v[74:77], v[178:181], v[202:205], v[74:77]
	v_mfma_f32_16x16x32_bf16 v[70:73], v[170:173], v[210:213], v[70:73]
	v_mfma_f32_16x16x32_bf16 v[66:69], v[178:181], v[210:213], v[66:69]
	v_mfma_f32_16x16x32_bf16 v[114:117], v[174:177], v[190:193], v[114:117]
	v_mfma_f32_16x16x32_bf16 v[106:109], v[182:185], v[190:193], v[106:109]
	v_mfma_f32_16x16x32_bf16 v[98:101], v[174:177], v[198:201], v[98:101]
	v_mfma_f32_16x16x32_bf16 v[90:93], v[182:185], v[198:201], v[90:93]
	s_setprio 3
	s_barrier
	v_mfma_f32_16x16x32_bf16 v[82:85], v[174:177], v[206:209], v[82:85]
	v_mfma_f32_16x16x32_bf16 v[74:77], v[182:185], v[206:209], v[74:77]
	v_mfma_f32_16x16x32_bf16 v[70:73], v[174:177], v[214:217], v[70:73]
	v_mfma_f32_16x16x32_bf16 v[66:69], v[182:185], v[214:217], v[66:69]
	s_setprio 0
	s_add_i32 s48, s70, s51
	v_lshl_add_u64 v[218:219], v[218:219], 0, s[28:29]
	s_mov_b32 m0, s48
	ds_read_b128 v[186:189], v156 offset:49152
	ds_read_b128 v[190:193], v156 offset:50176
	ds_read_b128 v[194:197], v156 offset:51200
	ds_read_b128 v[198:201], v156 offset:52224
	ds_read_b128 v[202:205], v156 offset:53248
	ds_read_b128 v[206:209], v156 offset:54272
	ds_read_b128 v[210:213], v156 offset:55296
	ds_read_b128 v[214:217], v156 offset:56320
	global_load_lds_dwordx4 v[218:219], off
	s_add_i32 m0, s48, 0x2000
	s_add_u32 s46, s46, 0x100080
	v_lshl_add_u64 v[218:219], v[220:221], 0, s[28:29]
	s_addc_u32 s47, s47, 0
	s_add_i32 s48, s71, s51
	global_load_lds_dwordx4 v[218:219], off
	v_lshl_add_u64 v[218:219], s[46:47], 0, v[134:135]
	s_mov_b32 m0, s48
	s_nop 0
	global_load_lds_dwordx4 v[218:219], off
	v_lshl_add_u64 v[218:219], s[46:47], 0, v[130:131]
	s_add_i32 m0, s48, 0x2000
	s_nop 0
	global_load_lds_dwordx4 v[218:219], off
	v_lshl_add_u64 v[218:219], v[222:223], 0, s[28:29]
	s_mov_b32 m0, s59
	s_nop 0
	global_load_lds_dwordx4 v[218:219], off
	v_lshl_add_u64 v[218:219], v[224:225], 0, s[28:29]
	s_mov_b32 m0, s60
	s_nop 0
	global_load_lds_dwordx4 v[218:219], off
	s_waitcnt vmcnt(8)
	s_waitcnt lgkmcnt(0)
	s_barrier
	s_setprio 1
	v_mfma_f32_16x16x32_bf16 v[62:65], v[148:151], v[186:189], v[62:65]
	v_mfma_f32_16x16x32_bf16 v[58:61], v[162:165], v[186:189], v[58:61]
	v_mfma_f32_16x16x32_bf16 v[54:57], v[148:151], v[194:197], v[54:57]
	v_mfma_f32_16x16x32_bf16 v[46:49], v[162:165], v[194:197], v[46:49]
	v_mfma_f32_16x16x32_bf16 v[38:41], v[148:151], v[202:205], v[38:41]
	v_mfma_f32_16x16x32_bf16 v[30:33], v[162:165], v[202:205], v[30:33]
	v_mfma_f32_16x16x32_bf16 v[22:25], v[148:151], v[210:213], v[22:25]
	v_mfma_f32_16x16x32_bf16 v[14:17], v[162:165], v[210:213], v[14:17]
	v_mfma_f32_16x16x32_bf16 v[62:65], v[158:161], v[190:193], v[62:65]
	v_mfma_f32_16x16x32_bf16 v[58:61], v[166:169], v[190:193], v[58:61]
	v_mfma_f32_16x16x32_bf16 v[54:57], v[158:161], v[198:201], v[54:57]
	v_mfma_f32_16x16x32_bf16 v[46:49], v[166:169], v[198:201], v[46:49]
	v_mfma_f32_16x16x32_bf16 v[38:41], v[158:161], v[206:209], v[38:41]
	v_mfma_f32_16x16x32_bf16 v[30:33], v[166:169], v[206:209], v[30:33]
	v_mfma_f32_16x16x32_bf16 v[22:25], v[158:161], v[214:217], v[22:25]
	v_mfma_f32_16x16x32_bf16 v[14:17], v[166:169], v[214:217], v[14:17]
	v_mfma_f32_16x16x32_bf16 v[50:53], v[170:173], v[186:189], v[50:53]
	v_mfma_f32_16x16x32_bf16 v[42:45], v[178:181], v[186:189], v[42:45]
	v_mfma_f32_16x16x32_bf16 v[34:37], v[170:173], v[194:197], v[34:37]
	v_mfma_f32_16x16x32_bf16 v[26:29], v[178:181], v[194:197], v[26:29]
	v_mfma_f32_16x16x32_bf16 v[18:21], v[170:173], v[202:205], v[18:21]
	v_mfma_f32_16x16x32_bf16 v[10:13], v[178:181], v[202:205], v[10:13]
	v_mfma_f32_16x16x32_bf16 v[6:9], v[170:173], v[210:213], v[6:9]
	v_mfma_f32_16x16x32_bf16 v[2:5], v[178:181], v[210:213], v[2:5]
	v_mfma_f32_16x16x32_bf16 v[50:53], v[174:177], v[190:193], v[50:53]
	v_mfma_f32_16x16x32_bf16 v[42:45], v[182:185], v[190:193], v[42:45]
	v_mfma_f32_16x16x32_bf16 v[34:37], v[174:177], v[198:201], v[34:37]
	v_mfma_f32_16x16x32_bf16 v[26:29], v[182:185], v[198:201], v[26:29]
	s_setprio 3
	s_barrier
	v_mfma_f32_16x16x32_bf16 v[18:21], v[174:177], v[206:209], v[18:21]
	v_mfma_f32_16x16x32_bf16 v[10:13], v[182:185], v[206:209], v[10:13]
	v_mfma_f32_16x16x32_bf16 v[6:9], v[174:177], v[214:217], v[6:9]
	v_mfma_f32_16x16x32_bf16 v[2:5], v[182:185], v[214:217], v[2:5]
	s_setprio 0
	s_add_i32 s69, s69, 2
	s_add_u32 s44, s44, 0x100
	s_addc_u32 s45, s45, 0
	s_add_u32 s67, s67, 0x100
	s_addc_u32 s68, s68, 0
	s_cmp_gt_u32 s69, 61
	s_cbranch_scc0 .LBB0_115
	s_and_b64 vcc, exec, s[30:31]
	s_cbranch_vccz .LBB0_118
	s_barrier

.LBB0_540:
	v_add_u32_e32 v139, s64, v186
	ds_read_b128 v[130:133], v139
	ds_read_b128 v[134:137], v139 offset:1024
	ds_read_b128 v[146:149], v139 offset:2048
	ds_read_b128 v[150:153], v139 offset:3072
	v_add_u32_e32 v139, s65, v186
	s_add_u32 s48, s44, s46
	ds_read_b128 v[154:157], v139
	ds_read_b128 v[174:177], v139 offset:1024
	ds_read_b128 v[178:181], v139 offset:2048
	ds_read_b128 v[182:185], v139 offset:3072
	s_addc_u32 s49, s45, s47
	s_add_u32 s48, s48, 0x100
	s_addc_u32 s49, s49, 0
	s_add_u32 s71, s68, s46
	s_addc_u32 s72, s69, s47
	s_cmpk_eq_i32 s46, 0x1f00
	s_cselect_b32 s51, s39, s49
	s_cselect_b32 s50, s66, s48
	s_cselect_b32 s49, s37, s72
	s_cselect_b32 s48, s67, s71
	v_lshl_add_u64 v[222:223], v[142:143], 0, s[46:47]
	s_add_i32 m0, s55, 0xc000
	ds_read_b128 v[190:193], v188
	ds_read_b128 v[194:197], v188 offset:1024
	ds_read_b128 v[198:201], v188 offset:2048
	ds_read_b128 v[202:205], v188 offset:3072
	ds_read_b128 v[206:209], v188 offset:4096
	ds_read_b128 v[210:213], v188 offset:5120
	ds_read_b128 v[214:217], v188 offset:6144
	ds_read_b128 v[218:221], v188 offset:7168
	global_load_lds_dwordx4 v[222:223], off
	v_lshl_add_u64 v[222:223], v[144:145], 0, s[46:47]
	s_add_i32 m0, s55, 0xe000
	s_nop 0
	global_load_lds_dwordx4 v[222:223], off
	s_waitcnt vmcnt(8)
	s_waitcnt lgkmcnt(0)
	s_barrier
	s_setprio 1
	v_mfma_f32_16x16x32_bf16 v[126:129], v[130:133], v[190:193], v[126:129]
	v_mfma_f32_16x16x32_bf16 v[122:125], v[146:149], v[190:193], v[122:125]
	v_mfma_f32_16x16x32_bf16 v[114:117], v[130:133], v[198:201], v[114:117]
	v_mfma_f32_16x16x32_bf16 v[106:109], v[146:149], v[198:201], v[106:109]
	v_mfma_f32_16x16x32_bf16 v[98:101], v[130:133], v[206:209], v[98:101]
	v_mfma_f32_16x16x32_bf16 v[90:93], v[146:149], v[206:209], v[90:93]
	v_mfma_f32_16x16x32_bf16 v[82:85], v[130:133], v[214:217], v[82:85]
	v_mfma_f32_16x16x32_bf16 v[74:77], v[146:149], v[214:217], v[74:77]
	v_mfma_f32_16x16x32_bf16 v[126:129], v[134:137], v[194:197], v[126:129]
	v_mfma_f32_16x16x32_bf16 v[122:125], v[150:153], v[194:197], v[122:125]
	v_mfma_f32_16x16x32_bf16 v[114:117], v[134:137], v[202:205], v[114:117]
	v_mfma_f32_16x16x32_bf16 v[106:109], v[150:153], v[202:205], v[106:109]
	v_mfma_f32_16x16x32_bf16 v[98:101], v[134:137], v[210:213], v[98:101]
	v_mfma_f32_16x16x32_bf16 v[90:93], v[150:153], v[210:213], v[90:93]
	v_mfma_f32_16x16x32_bf16 v[82:85], v[134:137], v[218:221], v[82:85]
	v_mfma_f32_16x16x32_bf16 v[74:77], v[150:153], v[218:221], v[74:77]
	v_mfma_f32_16x16x32_bf16 v[118:121], v[154:157], v[190:193], v[118:121]
	v_mfma_f32_16x16x32_bf16 v[110:113], v[178:181], v[190:193], v[110:113]
	v_mfma_f32_16x16x32_bf16 v[102:105], v[154:157], v[198:201], v[102:105]
	v_mfma_f32_16x16x32_bf16 v[94:97], v[178:181], v[198:201], v[94:97]
	v_mfma_f32_16x16x32_bf16 v[86:89], v[154:157], v[206:209], v[86:89]
	v_mfma_f32_16x16x32_bf16 v[78:81], v[178:181], v[206:209], v[78:81]
	v_mfma_f32_16x16x32_bf16 v[70:73], v[154:157], v[214:217], v[70:73]
	v_mfma_f32_16x16x32_bf16 v[66:69], v[178:181], v[214:217], v[66:69]
	v_mfma_f32_16x16x32_bf16 v[118:121], v[174:177], v[194:197], v[118:121]
	v_mfma_f32_16x16x32_bf16 v[110:113], v[182:185], v[194:197], v[110:113]
	v_mfma_f32_16x16x32_bf16 v[102:105], v[174:177], v[202:205], v[102:105]
	v_mfma_f32_16x16x32_bf16 v[94:97], v[182:185], v[202:205], v[94:97]
	s_setprio 3
	s_barrier
	v_mfma_f32_16x16x32_bf16 v[86:89], v[174:177], v[210:213], v[86:89]
	v_mfma_f32_16x16x32_bf16 v[78:81], v[182:185], v[210:213], v[78:81]
	v_mfma_f32_16x16x32_bf16 v[70:73], v[174:177], v[218:221], v[70:73]
	v_mfma_f32_16x16x32_bf16 v[66:69], v[182:185], v[218:221], v[66:69]
	s_setprio 0
	s_add_i32 s71, s64, s54
	v_lshl_add_u64 v[222:223], s[48:49], 0, v[160:161]
	s_mov_b32 m0, s71
	ds_read_b128 v[190:193], v188 offset:16384
	ds_read_b128 v[194:197], v188 offset:17408
	ds_read_b128 v[198:201], v188 offset:18432
	ds_read_b128 v[202:205], v188 offset:19456
	ds_read_b128 v[206:209], v188 offset:20480
	ds_read_b128 v[210:213], v188 offset:21504
	ds_read_b128 v[214:217], v188 offset:22528
	ds_read_b128 v[218:221], v188 offset:23552
	global_load_lds_dwordx4 v[222:223], off
	s_add_i32 m0, s71, 0x2000
	s_add_u32 s72, s48, 0x100000
	v_lshl_add_u64 v[224:225], s[48:49], 0, v[164:165]
	s_addc_u32 s73, s49, 0
	s_add_i32 s71, s65, s54
	global_load_lds_dwordx4 v[224:225], off
	v_lshl_add_u64 v[226:227], s[72:73], 0, v[160:161]
	s_mov_b32 m0, s71
	v_lshl_add_u64 v[228:229], s[50:51], 0, v[162:163]
	global_load_lds_dwordx4 v[226:227], off
	v_lshl_add_u64 v[226:227], s[72:73], 0, v[164:165]
	s_add_i32 m0, s71, 0x2000
	s_nop 0
	global_load_lds_dwordx4 v[226:227], off
	v_lshl_add_u64 v[226:227], s[50:51], 0, v[158:159]
	s_mov_b32 m0, s55
	s_nop 0
	global_load_lds_dwordx4 v[226:227], off
	s_mov_b32 m0, s56
	s_nop 0
	global_load_lds_dwordx4 v[228:229], off
	s_waitcnt vmcnt(8)
	s_waitcnt lgkmcnt(0)
	s_barrier
	s_setprio 1
	v_mfma_f32_16x16x32_bf16 v[62:65], v[130:133], v[190:193], v[62:65]
	v_mfma_f32_16x16x32_bf16 v[58:61], v[146:149], v[190:193], v[58:61]
	v_mfma_f32_16x16x32_bf16 v[50:53], v[130:133], v[198:201], v[50:53]
	v_mfma_f32_16x16x32_bf16 v[42:45], v[146:149], v[198:201], v[42:45]
	v_mfma_f32_16x16x32_bf16 v[34:37], v[130:133], v[206:209], v[34:37]
	v_mfma_f32_16x16x32_bf16 v[26:29], v[146:149], v[206:209], v[26:29]
	v_mfma_f32_16x16x32_bf16 v[18:21], v[130:133], v[214:217], v[18:21]
	v_mfma_f32_16x16x32_bf16 v[10:13], v[146:149], v[214:217], v[10:13]
	v_mfma_f32_16x16x32_bf16 v[62:65], v[134:137], v[194:197], v[62:65]
	v_mfma_f32_16x16x32_bf16 v[58:61], v[150:153], v[194:197], v[58:61]
	v_mfma_f32_16x16x32_bf16 v[50:53], v[134:137], v[202:205], v[50:53]
	v_mfma_f32_16x16x32_bf16 v[42:45], v[150:153], v[202:205], v[42:45]
	v_mfma_f32_16x16x32_bf16 v[34:37], v[134:137], v[210:213], v[34:37]
	v_mfma_f32_16x16x32_bf16 v[26:29], v[150:153], v[210:213], v[26:29]
	v_mfma_f32_16x16x32_bf16 v[18:21], v[134:137], v[218:221], v[18:21]
	v_mfma_f32_16x16x32_bf16 v[10:13], v[150:153], v[218:221], v[10:13]
	v_mfma_f32_16x16x32_bf16 v[54:57], v[154:157], v[190:193], v[54:57]
	v_mfma_f32_16x16x32_bf16 v[46:49], v[178:181], v[190:193], v[46:49]
	v_mfma_f32_16x16x32_bf16 v[38:41], v[154:157], v[198:201], v[38:41]
	v_mfma_f32_16x16x32_bf16 v[30:33], v[178:181], v[198:201], v[30:33]
	v_mfma_f32_16x16x32_bf16 v[22:25], v[154:157], v[206:209], v[22:25]
	v_mfma_f32_16x16x32_bf16 v[14:17], v[178:181], v[206:209], v[14:17]
	v_mfma_f32_16x16x32_bf16 v[6:9], v[154:157], v[214:217], v[6:9]
	v_mfma_f32_16x16x32_bf16 v[2:5], v[178:181], v[214:217], v[2:5]
	v_mfma_f32_16x16x32_bf16 v[54:57], v[174:177], v[194:197], v[54:57]
	v_mfma_f32_16x16x32_bf16 v[46:49], v[182:185], v[194:197], v[46:49]
	v_mfma_f32_16x16x32_bf16 v[38:41], v[174:177], v[202:205], v[38:41]
	v_mfma_f32_16x16x32_bf16 v[30:33], v[182:185], v[202:205], v[30:33]
	s_setprio 3
	s_barrier
	v_mfma_f32_16x16x32_bf16 v[22:25], v[174:177], v[210:213], v[22:25]
	v_mfma_f32_16x16x32_bf16 v[14:17], v[182:185], v[210:213], v[14:17]
	v_mfma_f32_16x16x32_bf16 v[6:9], v[174:177], v[218:221], v[6:9]
	v_mfma_f32_16x16x32_bf16 v[2:5], v[182:185], v[218:221], v[2:5]
	s_setprio 0
	s_add_i32 s71, 0, 0x18000
	v_add_u32_e32 v139, s71, v186
	s_add_i32 s72, 0, 0x1c000
	ds_read_b128 v[130:133], v139
	ds_read_b128 v[134:137], v139 offset:1024
	ds_read_b128 v[146:149], v139 offset:2048
	ds_read_b128 v[150:153], v139 offset:3072
	v_add_u32_e32 v139, s72, v186
	ds_read_b128 v[154:157], v139
	ds_read_b128 v[174:177], v139 offset:1024
	ds_read_b128 v[178:181], v139 offset:2048
	ds_read_b128 v[182:185], v139 offset:3072
	s_add_u32 s50, s50, 0x100000
	s_addc_u32 s51, s51, 0
	s_mov_b32 m0, s57
	v_lshl_add_u64 v[230:231], s[50:51], 0, v[158:159]
	ds_read_b128 v[190:193], v188 offset:32768
	ds_read_b128 v[194:197], v188 offset:33792
	ds_read_b128 v[198:201], v188 offset:34816
	ds_read_b128 v[202:205], v188 offset:35840
	ds_read_b128 v[206:209], v188 offset:36864
	ds_read_b128 v[210:213], v188 offset:37888
	ds_read_b128 v[214:217], v188 offset:38912
	ds_read_b128 v[218:221], v188 offset:39936
	global_load_lds_dwordx4 v[230:231], off
	v_lshl_add_u64 v[230:231], s[50:51], 0, v[162:163]
	s_mov_b32 m0, s58
	s_nop 0
	global_load_lds_dwordx4 v[230:231], off
	s_waitcnt vmcnt(8)
	s_waitcnt lgkmcnt(0)
	s_barrier
	s_setprio 1
	v_mfma_f32_16x16x32_bf16 v[126:129], v[130:133], v[190:193], v[126:129]
	v_mfma_f32_16x16x32_bf16 v[122:125], v[146:149], v[190:193], v[122:125]
	v_mfma_f32_16x16x32_bf16 v[114:117], v[130:133], v[198:201], v[114:117]
	v_mfma_f32_16x16x32_bf16 v[106:109], v[146:149], v[198:201], v[106:109]
	v_mfma_f32_16x16x32_bf16 v[98:101], v[130:133], v[206:209], v[98:101]
	v_mfma_f32_16x16x32_bf16 v[90:93], v[146:149], v[206:209], v[90:93]
	v_mfma_f32_16x16x32_bf16 v[82:85], v[130:133], v[214:217], v[82:85]
	v_mfma_f32_16x16x32_bf16 v[74:77], v[146:149], v[214:217], v[74:77]
	v_mfma_f32_16x16x32_bf16 v[126:129], v[134:137], v[194:197], v[126:129]
	v_mfma_f32_16x16x32_bf16 v[122:125], v[150:153], v[194:197], v[122:125]
	v_mfma_f32_16x16x32_bf16 v[114:117], v[134:137], v[202:205], v[114:117]
	v_mfma_f32_16x16x32_bf16 v[106:109], v[150:153], v[202:205], v[106:109]
	v_mfma_f32_16x16x32_bf16 v[98:101], v[134:137], v[210:213], v[98:101]
	v_mfma_f32_16x16x32_bf16 v[90:93], v[150:153], v[210:213], v[90:93]
	v_mfma_f32_16x16x32_bf16 v[82:85], v[134:137], v[218:221], v[82:85]
	v_mfma_f32_16x16x32_bf16 v[74:77], v[150:153], v[218:221], v[74:77]
	v_mfma_f32_16x16x32_bf16 v[118:121], v[154:157], v[190:193], v[118:121]
	v_mfma_f32_16x16x32_bf16 v[110:113], v[178:181], v[190:193], v[110:113]
	v_mfma_f32_16x16x32_bf16 v[102:105], v[154:157], v[198:201], v[102:105]
	v_mfma_f32_16x16x32_bf16 v[94:97], v[178:181], v[198:201], v[94:97]
	v_mfma_f32_16x16x32_bf16 v[86:89], v[154:157], v[206:209], v[86:89]
	v_mfma_f32_16x16x32_bf16 v[78:81], v[178:181], v[206:209], v[78:81]
	v_mfma_f32_16x16x32_bf16 v[70:73], v[154:157], v[214:217], v[70:73]
	v_mfma_f32_16x16x32_bf16 v[66:69], v[178:181], v[214:217], v[66:69]
	v_mfma_f32_16x16x32_bf16 v[118:121], v[174:177], v[194:197], v[118:121]
	v_mfma_f32_16x16x32_bf16 v[110:113], v[182:185], v[194:197], v[110:113]
	v_mfma_f32_16x16x32_bf16 v[102:105], v[174:177], v[202:205], v[102:105]
	v_mfma_f32_16x16x32_bf16 v[94:97], v[182:185], v[202:205], v[94:97]
	s_setprio 3
	s_barrier
	v_mfma_f32_16x16x32_bf16 v[86:89], v[174:177], v[210:213], v[86:89]
	v_mfma_f32_16x16x32_bf16 v[78:81], v[182:185], v[210:213], v[78:81]
	v_mfma_f32_16x16x32_bf16 v[70:73], v[174:177], v[218:221], v[70:73]
	v_mfma_f32_16x16x32_bf16 v[66:69], v[182:185], v[218:221], v[66:69]
	s_setprio 0
	s_add_i32 s50, s71, s54
	v_lshl_add_u64 v[222:223], v[222:223], 0, s[30:31]
	s_mov_b32 m0, s50
	ds_read_b128 v[190:193], v188 offset:49152
	ds_read_b128 v[194:197], v188 offset:50176
	ds_read_b128 v[198:201], v188 offset:51200
	ds_read_b128 v[202:205], v188 offset:52224
	ds_read_b128 v[206:209], v188 offset:53248
	ds_read_b128 v[210:213], v188 offset:54272
	ds_read_b128 v[214:217], v188 offset:55296
	ds_read_b128 v[218:221], v188 offset:56320
	global_load_lds_dwordx4 v[222:223], off
	s_add_i32 m0, s50, 0x2000
	s_add_u32 s48, s48, 0x100080
	v_lshl_add_u64 v[222:223], v[224:225], 0, s[30:31]
	s_addc_u32 s49, s49, 0
	s_add_i32 s50, s72, s54
	global_load_lds_dwordx4 v[222:223], off
	v_lshl_add_u64 v[222:223], s[48:49], 0, v[160:161]
	s_mov_b32 m0, s50
	s_nop 0
	global_load_lds_dwordx4 v[222:223], off
	v_lshl_add_u64 v[222:223], s[48:49], 0, v[164:165]
	s_add_i32 m0, s50, 0x2000
	s_nop 0
	global_load_lds_dwordx4 v[222:223], off
	v_lshl_add_u64 v[222:223], v[226:227], 0, s[30:31]
	s_mov_b32 m0, s60
	s_nop 0
	global_load_lds_dwordx4 v[222:223], off
	v_lshl_add_u64 v[222:223], v[228:229], 0, s[30:31]
	s_mov_b32 m0, s61
	s_nop 0
	global_load_lds_dwordx4 v[222:223], off
	s_waitcnt vmcnt(8)
	s_waitcnt lgkmcnt(0)
	s_barrier
	s_setprio 1
	v_mfma_f32_16x16x32_bf16 v[62:65], v[130:133], v[190:193], v[62:65]
	v_mfma_f32_16x16x32_bf16 v[58:61], v[146:149], v[190:193], v[58:61]
	v_mfma_f32_16x16x32_bf16 v[50:53], v[130:133], v[198:201], v[50:53]
	v_mfma_f32_16x16x32_bf16 v[42:45], v[146:149], v[198:201], v[42:45]
	v_mfma_f32_16x16x32_bf16 v[34:37], v[130:133], v[206:209], v[34:37]
	v_mfma_f32_16x16x32_bf16 v[26:29], v[146:149], v[206:209], v[26:29]
	v_mfma_f32_16x16x32_bf16 v[18:21], v[130:133], v[214:217], v[18:21]
	v_mfma_f32_16x16x32_bf16 v[10:13], v[146:149], v[214:217], v[10:13]
	v_mfma_f32_16x16x32_bf16 v[62:65], v[134:137], v[194:197], v[62:65]
	v_mfma_f32_16x16x32_bf16 v[58:61], v[150:153], v[194:197], v[58:61]
	v_mfma_f32_16x16x32_bf16 v[50:53], v[134:137], v[202:205], v[50:53]
	v_mfma_f32_16x16x32_bf16 v[42:45], v[150:153], v[202:205], v[42:45]
	v_mfma_f32_16x16x32_bf16 v[34:37], v[134:137], v[210:213], v[34:37]
	v_mfma_f32_16x16x32_bf16 v[26:29], v[150:153], v[210:213], v[26:29]
	v_mfma_f32_16x16x32_bf16 v[18:21], v[134:137], v[218:221], v[18:21]
	v_mfma_f32_16x16x32_bf16 v[10:13], v[150:153], v[218:221], v[10:13]
	v_mfma_f32_16x16x32_bf16 v[54:57], v[154:157], v[190:193], v[54:57]
	v_mfma_f32_16x16x32_bf16 v[46:49], v[178:181], v[190:193], v[46:49]
	v_mfma_f32_16x16x32_bf16 v[38:41], v[154:157], v[198:201], v[38:41]
	v_mfma_f32_16x16x32_bf16 v[30:33], v[178:181], v[198:201], v[30:33]
	v_mfma_f32_16x16x32_bf16 v[22:25], v[154:157], v[206:209], v[22:25]
	v_mfma_f32_16x16x32_bf16 v[14:17], v[178:181], v[206:209], v[14:17]
	v_mfma_f32_16x16x32_bf16 v[6:9], v[154:157], v[214:217], v[6:9]
	v_mfma_f32_16x16x32_bf16 v[2:5], v[178:181], v[214:217], v[2:5]
	v_mfma_f32_16x16x32_bf16 v[54:57], v[174:177], v[194:197], v[54:57]
	v_mfma_f32_16x16x32_bf16 v[46:49], v[182:185], v[194:197], v[46:49]
	v_mfma_f32_16x16x32_bf16 v[38:41], v[174:177], v[202:205], v[38:41]
	v_mfma_f32_16x16x32_bf16 v[30:33], v[182:185], v[202:205], v[30:33]
	s_setprio 3
	s_barrier
	v_mfma_f32_16x16x32_bf16 v[22:25], v[174:177], v[210:213], v[22:25]
	v_mfma_f32_16x16x32_bf16 v[14:17], v[182:185], v[210:213], v[14:17]
	v_mfma_f32_16x16x32_bf16 v[6:9], v[174:177], v[218:221], v[6:9]
	v_mfma_f32_16x16x32_bf16 v[2:5], v[182:185], v[218:221], v[2:5]
	s_setprio 0
	s_add_i32 s70, s70, 2
	s_add_u32 s46, s46, 0x100
	s_addc_u32 s47, s47, 0
	s_cmp_gt_u32 s70, 61
	s_cbranch_scc1 .LBB0_543

.LBB0_618:
	ds_read_b128 v[146:149], v154
	ds_read_b128 v[158:161], v154 offset:1024
	ds_read_b128 v[162:165], v154 offset:2048
	ds_read_b128 v[166:169], v154 offset:3072
	ds_read_b128 v[170:173], v155
	ds_read_b128 v[174:177], v155 offset:1024
	ds_read_b128 v[178:181], v155 offset:2048
	ds_read_b128 v[182:185], v155 offset:3072
	s_add_u32 s48, s46, 0xfff00080
	s_addc_u32 s49, s47, -1
	s_cmp_eq_u32 s68, 60
	s_cselect_b32 s51, s39, s49
	s_cselect_b32 s50, s64, s48
	s_cselect_b32 s49, s37, s67
	s_cselect_b32 s48, s65, s66
	v_lshl_add_u64 v[150:151], s[46:47], 0, v[138:139]
	s_add_i32 m0, s45, 0xc000
	ds_read_b128 v[186:189], v156
	ds_read_b128 v[190:193], v156 offset:1024
	ds_read_b128 v[194:197], v156 offset:2048
	ds_read_b128 v[198:201], v156 offset:3072
	ds_read_b128 v[202:205], v156 offset:4096
	ds_read_b128 v[206:209], v156 offset:5120
	ds_read_b128 v[210:213], v156 offset:6144
	ds_read_b128 v[214:217], v156 offset:7168
	global_load_lds_dwordx4 v[150:151], off
	v_lshl_add_u64 v[150:151], s[46:47], 0, v[140:141]
	s_add_i32 m0, s45, 0xe000
	s_nop 0
	global_load_lds_dwordx4 v[150:151], off
	s_waitcnt vmcnt(8)
	s_waitcnt lgkmcnt(0)
	s_barrier
	s_setprio 1
	v_mfma_f32_16x16x32_bf16 v[126:129], v[146:149], v[186:189], v[126:129]
	v_mfma_f32_16x16x32_bf16 v[122:125], v[162:165], v[186:189], v[122:125]
	v_mfma_f32_16x16x32_bf16 v[118:121], v[146:149], v[194:197], v[118:121]
	v_mfma_f32_16x16x32_bf16 v[114:117], v[162:165], v[194:197], v[114:117]
	v_mfma_f32_16x16x32_bf16 v[102:105], v[146:149], v[202:205], v[102:105]
	v_mfma_f32_16x16x32_bf16 v[98:101], v[162:165], v[202:205], v[98:101]
	v_mfma_f32_16x16x32_bf16 v[86:89], v[146:149], v[210:213], v[86:89]
	v_mfma_f32_16x16x32_bf16 v[78:81], v[162:165], v[210:213], v[78:81]
	v_mfma_f32_16x16x32_bf16 v[126:129], v[158:161], v[190:193], v[126:129]
	v_mfma_f32_16x16x32_bf16 v[122:125], v[166:169], v[190:193], v[122:125]
	v_mfma_f32_16x16x32_bf16 v[118:121], v[158:161], v[198:201], v[118:121]
	v_mfma_f32_16x16x32_bf16 v[114:117], v[166:169], v[198:201], v[114:117]
	v_mfma_f32_16x16x32_bf16 v[102:105], v[158:161], v[206:209], v[102:105]
	v_mfma_f32_16x16x32_bf16 v[98:101], v[166:169], v[206:209], v[98:101]
	v_mfma_f32_16x16x32_bf16 v[86:89], v[158:161], v[214:217], v[86:89]
	v_mfma_f32_16x16x32_bf16 v[78:81], v[166:169], v[214:217], v[78:81]
	v_mfma_f32_16x16x32_bf16 v[110:113], v[170:173], v[186:189], v[110:113]
	v_mfma_f32_16x16x32_bf16 v[106:109], v[178:181], v[186:189], v[106:109]
	v_mfma_f32_16x16x32_bf16 v[94:97], v[170:173], v[194:197], v[94:97]
	v_mfma_f32_16x16x32_bf16 v[90:93], v[178:181], v[194:197], v[90:93]
	v_mfma_f32_16x16x32_bf16 v[82:85], v[170:173], v[202:205], v[82:85]
	v_mfma_f32_16x16x32_bf16 v[74:77], v[178:181], v[202:205], v[74:77]
	v_mfma_f32_16x16x32_bf16 v[70:73], v[170:173], v[210:213], v[70:73]
	v_mfma_f32_16x16x32_bf16 v[66:69], v[178:181], v[210:213], v[66:69]
	v_mfma_f32_16x16x32_bf16 v[110:113], v[174:177], v[190:193], v[110:113]
	v_mfma_f32_16x16x32_bf16 v[106:109], v[182:185], v[190:193], v[106:109]
	v_mfma_f32_16x16x32_bf16 v[94:97], v[174:177], v[198:201], v[94:97]
	v_mfma_f32_16x16x32_bf16 v[90:93], v[182:185], v[198:201], v[90:93]
	s_setprio 3
	s_barrier
	v_mfma_f32_16x16x32_bf16 v[82:85], v[174:177], v[206:209], v[82:85]
	v_mfma_f32_16x16x32_bf16 v[74:77], v[182:185], v[206:209], v[74:77]
	v_mfma_f32_16x16x32_bf16 v[70:73], v[174:177], v[214:217], v[70:73]
	v_mfma_f32_16x16x32_bf16 v[66:69], v[182:185], v[214:217], v[66:69]
	s_setprio 0
	s_add_i32 s69, s61, s53
	v_lshl_add_u64 v[150:151], s[48:49], 0, v[132:133]
	s_mov_b32 m0, s69
	ds_read_b128 v[186:189], v156 offset:16384
	ds_read_b128 v[190:193], v156 offset:17408
	ds_read_b128 v[194:197], v156 offset:18432
	ds_read_b128 v[198:201], v156 offset:19456
	ds_read_b128 v[202:205], v156 offset:20480
	ds_read_b128 v[206:209], v156 offset:21504
	ds_read_b128 v[210:213], v156 offset:22528
	ds_read_b128 v[214:217], v156 offset:23552
	global_load_lds_dwordx4 v[150:151], off
	s_add_i32 m0, s69, 0x2000
	s_add_u32 s70, s48, 0x100000
	v_lshl_add_u64 v[218:219], s[48:49], 0, v[136:137]
	s_addc_u32 s71, s49, 0
	s_add_i32 s69, s62, s53
	global_load_lds_dwordx4 v[218:219], off
	v_lshl_add_u64 v[220:221], s[70:71], 0, v[132:133]
	s_mov_b32 m0, s69
	v_lshl_add_u64 v[222:223], s[50:51], 0, v[134:135]
	global_load_lds_dwordx4 v[220:221], off
	v_lshl_add_u64 v[220:221], s[70:71], 0, v[136:137]
	s_add_i32 m0, s69, 0x2000
	s_nop 0
	global_load_lds_dwordx4 v[220:221], off
	v_lshl_add_u64 v[220:221], s[50:51], 0, v[130:131]
	s_mov_b32 m0, s45
	s_nop 0
	global_load_lds_dwordx4 v[220:221], off
	s_mov_b32 m0, s54
	s_nop 0
	global_load_lds_dwordx4 v[222:223], off
	s_waitcnt vmcnt(8)
	s_waitcnt lgkmcnt(0)
	s_barrier
	s_setprio 1
	v_mfma_f32_16x16x32_bf16 v[62:65], v[146:149], v[186:189], v[62:65]
	v_mfma_f32_16x16x32_bf16 v[58:61], v[162:165], v[186:189], v[58:61]
	v_mfma_f32_16x16x32_bf16 v[50:53], v[146:149], v[194:197], v[50:53]
	v_mfma_f32_16x16x32_bf16 v[42:45], v[162:165], v[194:197], v[42:45]
	v_mfma_f32_16x16x32_bf16 v[38:41], v[146:149], v[202:205], v[38:41]
	v_mfma_f32_16x16x32_bf16 v[30:33], v[162:165], v[202:205], v[30:33]
	v_mfma_f32_16x16x32_bf16 v[22:25], v[146:149], v[210:213], v[22:25]
	v_mfma_f32_16x16x32_bf16 v[14:17], v[162:165], v[210:213], v[14:17]
	v_mfma_f32_16x16x32_bf16 v[62:65], v[158:161], v[190:193], v[62:65]
	v_mfma_f32_16x16x32_bf16 v[58:61], v[166:169], v[190:193], v[58:61]
	v_mfma_f32_16x16x32_bf16 v[50:53], v[158:161], v[198:201], v[50:53]
	v_mfma_f32_16x16x32_bf16 v[42:45], v[166:169], v[198:201], v[42:45]
	v_mfma_f32_16x16x32_bf16 v[38:41], v[158:161], v[206:209], v[38:41]
	v_mfma_f32_16x16x32_bf16 v[30:33], v[166:169], v[206:209], v[30:33]
	v_mfma_f32_16x16x32_bf16 v[22:25], v[158:161], v[214:217], v[22:25]
	v_mfma_f32_16x16x32_bf16 v[14:17], v[166:169], v[214:217], v[14:17]
	v_mfma_f32_16x16x32_bf16 v[54:57], v[170:173], v[186:189], v[54:57]
	v_mfma_f32_16x16x32_bf16 v[46:49], v[178:181], v[186:189], v[46:49]
	v_mfma_f32_16x16x32_bf16 v[34:37], v[170:173], v[194:197], v[34:37]
	v_mfma_f32_16x16x32_bf16 v[26:29], v[178:181], v[194:197], v[26:29]
	v_mfma_f32_16x16x32_bf16 v[18:21], v[170:173], v[202:205], v[18:21]
	v_mfma_f32_16x16x32_bf16 v[10:13], v[178:181], v[202:205], v[10:13]
	v_mfma_f32_16x16x32_bf16 v[6:9], v[170:173], v[210:213], v[6:9]
	v_mfma_f32_16x16x32_bf16 v[2:5], v[178:181], v[210:213], v[2:5]
	v_mfma_f32_16x16x32_bf16 v[54:57], v[174:177], v[190:193], v[54:57]
	v_mfma_f32_16x16x32_bf16 v[46:49], v[182:185], v[190:193], v[46:49]
	v_mfma_f32_16x16x32_bf16 v[34:37], v[174:177], v[198:201], v[34:37]
	v_mfma_f32_16x16x32_bf16 v[26:29], v[182:185], v[198:201], v[26:29]
	s_setprio 3
	s_barrier
	v_mfma_f32_16x16x32_bf16 v[18:21], v[174:177], v[206:209], v[18:21]
	v_mfma_f32_16x16x32_bf16 v[10:13], v[182:185], v[206:209], v[10:13]
	v_mfma_f32_16x16x32_bf16 v[6:9], v[174:177], v[214:217], v[6:9]
	v_mfma_f32_16x16x32_bf16 v[2:5], v[182:185], v[214:217], v[2:5]
	s_setprio 0
	s_add_i32 s69, 0, 0x18000
	v_add_u32_e32 v157, s69, v152
	s_add_i32 s70, 0, 0x1c000
	ds_read_b128 v[146:149], v157
	ds_read_b128 v[158:161], v157 offset:1024
	ds_read_b128 v[162:165], v157 offset:2048
	ds_read_b128 v[166:169], v157 offset:3072
	v_add_u32_e32 v157, s70, v152
	ds_read_b128 v[170:173], v157
	ds_read_b128 v[174:177], v157 offset:1024
	ds_read_b128 v[178:181], v157 offset:2048
	ds_read_b128 v[182:185], v157 offset:3072
	s_add_u32 s50, s50, 0x100000
	s_addc_u32 s51, s51, 0
	s_mov_b32 m0, s55
	v_lshl_add_u64 v[224:225], s[50:51], 0, v[130:131]
	ds_read_b128 v[186:189], v156 offset:32768
	ds_read_b128 v[190:193], v156 offset:33792
	ds_read_b128 v[194:197], v156 offset:34816
	ds_read_b128 v[198:201], v156 offset:35840
	ds_read_b128 v[202:205], v156 offset:36864
	ds_read_b128 v[206:209], v156 offset:37888
	ds_read_b128 v[210:213], v156 offset:38912
	ds_read_b128 v[214:217], v156 offset:39936
	global_load_lds_dwordx4 v[224:225], off
	v_lshl_add_u64 v[224:225], s[50:51], 0, v[134:135]
	s_mov_b32 m0, s56
	s_nop 0
	global_load_lds_dwordx4 v[224:225], off
	s_waitcnt vmcnt(8)
	s_waitcnt lgkmcnt(0)
	s_barrier
	s_setprio 1
	v_mfma_f32_16x16x32_bf16 v[126:129], v[146:149], v[186:189], v[126:129]
	v_mfma_f32_16x16x32_bf16 v[122:125], v[162:165], v[186:189], v[122:125]
	v_mfma_f32_16x16x32_bf16 v[118:121], v[146:149], v[194:197], v[118:121]
	v_mfma_f32_16x16x32_bf16 v[114:117], v[162:165], v[194:197], v[114:117]
	v_mfma_f32_16x16x32_bf16 v[102:105], v[146:149], v[202:205], v[102:105]
	v_mfma_f32_16x16x32_bf16 v[98:101], v[162:165], v[202:205], v[98:101]
	v_mfma_f32_16x16x32_bf16 v[86:89], v[146:149], v[210:213], v[86:89]
	v_mfma_f32_16x16x32_bf16 v[78:81], v[162:165], v[210:213], v[78:81]
	v_mfma_f32_16x16x32_bf16 v[126:129], v[158:161], v[190:193], v[126:129]
	v_mfma_f32_16x16x32_bf16 v[122:125], v[166:169], v[190:193], v[122:125]
	v_mfma_f32_16x16x32_bf16 v[118:121], v[158:161], v[198:201], v[118:121]
	v_mfma_f32_16x16x32_bf16 v[114:117], v[166:169], v[198:201], v[114:117]
	v_mfma_f32_16x16x32_bf16 v[102:105], v[158:161], v[206:209], v[102:105]
	v_mfma_f32_16x16x32_bf16 v[98:101], v[166:169], v[206:209], v[98:101]
	v_mfma_f32_16x16x32_bf16 v[86:89], v[158:161], v[214:217], v[86:89]
	v_mfma_f32_16x16x32_bf16 v[78:81], v[166:169], v[214:217], v[78:81]
	v_mfma_f32_16x16x32_bf16 v[110:113], v[170:173], v[186:189], v[110:113]
	v_mfma_f32_16x16x32_bf16 v[106:109], v[178:181], v[186:189], v[106:109]
	v_mfma_f32_16x16x32_bf16 v[94:97], v[170:173], v[194:197], v[94:97]
	v_mfma_f32_16x16x32_bf16 v[90:93], v[178:181], v[194:197], v[90:93]
	v_mfma_f32_16x16x32_bf16 v[82:85], v[170:173], v[202:205], v[82:85]
	v_mfma_f32_16x16x32_bf16 v[74:77], v[178:181], v[202:205], v[74:77]
	v_mfma_f32_16x16x32_bf16 v[70:73], v[170:173], v[210:213], v[70:73]
	v_mfma_f32_16x16x32_bf16 v[66:69], v[178:181], v[210:213], v[66:69]
	v_mfma_f32_16x16x32_bf16 v[110:113], v[174:177], v[190:193], v[110:113]
	v_mfma_f32_16x16x32_bf16 v[106:109], v[182:185], v[190:193], v[106:109]
	v_mfma_f32_16x16x32_bf16 v[94:97], v[174:177], v[198:201], v[94:97]
	v_mfma_f32_16x16x32_bf16 v[90:93], v[182:185], v[198:201], v[90:93]
	s_setprio 3
	s_barrier
	v_mfma_f32_16x16x32_bf16 v[82:85], v[174:177], v[206:209], v[82:85]
	v_mfma_f32_16x16x32_bf16 v[74:77], v[182:185], v[206:209], v[74:77]
	v_mfma_f32_16x16x32_bf16 v[70:73], v[174:177], v[214:217], v[70:73]
	v_mfma_f32_16x16x32_bf16 v[66:69], v[182:185], v[214:217], v[66:69]
	s_setprio 0
	s_add_i32 s50, s69, s53
	v_lshl_add_u64 v[150:151], v[150:151], 0, s[28:29]
	s_mov_b32 m0, s50
	ds_read_b128 v[186:189], v156 offset:49152
	ds_read_b128 v[190:193], v156 offset:50176
	ds_read_b128 v[194:197], v156 offset:51200
	ds_read_b128 v[198:201], v156 offset:52224
	ds_read_b128 v[202:205], v156 offset:53248
	ds_read_b128 v[206:209], v156 offset:54272
	ds_read_b128 v[210:213], v156 offset:55296
	ds_read_b128 v[214:217], v156 offset:56320
	global_load_lds_dwordx4 v[150:151], off
	s_add_i32 m0, s50, 0x2000
	s_add_u32 s48, s48, 0x100080
	v_lshl_add_u64 v[150:151], v[218:219], 0, s[28:29]
	s_addc_u32 s49, s49, 0
	s_add_i32 s50, s70, s53
	global_load_lds_dwordx4 v[150:151], off
	v_lshl_add_u64 v[150:151], s[48:49], 0, v[132:133]
	s_mov_b32 m0, s50
	s_nop 0
	global_load_lds_dwordx4 v[150:151], off
	v_lshl_add_u64 v[150:151], s[48:49], 0, v[136:137]
	s_add_i32 m0, s50, 0x2000
	s_nop 0
	global_load_lds_dwordx4 v[150:151], off
	v_lshl_add_u64 v[150:151], v[220:221], 0, s[28:29]
	s_mov_b32 m0, s58
	s_nop 0
	global_load_lds_dwordx4 v[150:151], off
	v_lshl_add_u64 v[150:151], v[222:223], 0, s[28:29]
	s_mov_b32 m0, s59
	s_nop 0
	global_load_lds_dwordx4 v[150:151], off
	s_waitcnt vmcnt(8)
	s_waitcnt lgkmcnt(0)
	s_barrier
	s_setprio 1
	v_mfma_f32_16x16x32_bf16 v[62:65], v[146:149], v[186:189], v[62:65]
	v_mfma_f32_16x16x32_bf16 v[58:61], v[162:165], v[186:189], v[58:61]
	v_mfma_f32_16x16x32_bf16 v[50:53], v[146:149], v[194:197], v[50:53]
	v_mfma_f32_16x16x32_bf16 v[42:45], v[162:165], v[194:197], v[42:45]
	v_mfma_f32_16x16x32_bf16 v[38:41], v[146:149], v[202:205], v[38:41]
	v_mfma_f32_16x16x32_bf16 v[30:33], v[162:165], v[202:205], v[30:33]
	v_mfma_f32_16x16x32_bf16 v[22:25], v[146:149], v[210:213], v[22:25]
	v_mfma_f32_16x16x32_bf16 v[14:17], v[162:165], v[210:213], v[14:17]
	v_mfma_f32_16x16x32_bf16 v[62:65], v[158:161], v[190:193], v[62:65]
	v_mfma_f32_16x16x32_bf16 v[58:61], v[166:169], v[190:193], v[58:61]
	v_mfma_f32_16x16x32_bf16 v[50:53], v[158:161], v[198:201], v[50:53]
	v_mfma_f32_16x16x32_bf16 v[42:45], v[166:169], v[198:201], v[42:45]
	v_mfma_f32_16x16x32_bf16 v[38:41], v[158:161], v[206:209], v[38:41]
	v_mfma_f32_16x16x32_bf16 v[30:33], v[166:169], v[206:209], v[30:33]
	v_mfma_f32_16x16x32_bf16 v[22:25], v[158:161], v[214:217], v[22:25]
	v_mfma_f32_16x16x32_bf16 v[14:17], v[166:169], v[214:217], v[14:17]
	v_mfma_f32_16x16x32_bf16 v[54:57], v[170:173], v[186:189], v[54:57]
	v_mfma_f32_16x16x32_bf16 v[46:49], v[178:181], v[186:189], v[46:49]
	v_mfma_f32_16x16x32_bf16 v[34:37], v[170:173], v[194:197], v[34:37]
	v_mfma_f32_16x16x32_bf16 v[26:29], v[178:181], v[194:197], v[26:29]
	v_mfma_f32_16x16x32_bf16 v[18:21], v[170:173], v[202:205], v[18:21]
	v_mfma_f32_16x16x32_bf16 v[10:13], v[178:181], v[202:205], v[10:13]
	v_mfma_f32_16x16x32_bf16 v[6:9], v[170:173], v[210:213], v[6:9]
	v_mfma_f32_16x16x32_bf16 v[2:5], v[178:181], v[210:213], v[2:5]
	v_mfma_f32_16x16x32_bf16 v[54:57], v[174:177], v[190:193], v[54:57]
	v_mfma_f32_16x16x32_bf16 v[46:49], v[182:185], v[190:193], v[46:49]
	v_mfma_f32_16x16x32_bf16 v[34:37], v[174:177], v[198:201], v[34:37]
	v_mfma_f32_16x16x32_bf16 v[26:29], v[182:185], v[198:201], v[26:29]
	s_setprio 3
	s_barrier
	v_mfma_f32_16x16x32_bf16 v[18:21], v[174:177], v[206:209], v[18:21]
	v_mfma_f32_16x16x32_bf16 v[10:13], v[182:185], v[206:209], v[10:13]
	v_mfma_f32_16x16x32_bf16 v[6:9], v[174:177], v[214:217], v[6:9]
	v_mfma_f32_16x16x32_bf16 v[2:5], v[182:185], v[214:217], v[2:5]
	s_setprio 0
	s_add_i32 s68, s68, 2
	s_add_u32 s46, s46, 0x100
	s_addc_u32 s47, s47, 0
	s_add_u32 s66, s66, 0x100
	s_addc_u32 s67, s67, 0
	s_cmp_gt_u32 s68, 61
	s_cbranch_scc0 .LBB0_618
	s_and_b64 vcc, exec, s[30:31]
	s_cbranch_vccz .LBB0_621
	s_barrier

.LBB0_743:
	ds_read_b128 v[130:133], v197
	ds_read_b128 v[134:137], v197 offset:1024
	ds_read_b128 v[138:141], v197 offset:2048
	ds_read_b128 v[142:145], v197 offset:3072
	ds_read_b128 v[146:149], v198
	ds_read_b128 v[150:153], v198 offset:1024
	ds_read_b128 v[154:157], v198 offset:2048
	ds_read_b128 v[158:161], v198 offset:3072
	s_add_u32 s72, s70, 0xfff00080
	s_addc_u32 s73, s71, -1
	s_cmp_eq_u32 s95, 60
	s_cselect_b32 s75, s61, s73
	s_cselect_b32 s74, s67, s72
	s_cselect_b32 s73, s59, s94
	s_cselect_b32 s72, s69, s93
	v_lshl_add_u64 v[184:185], s[70:71], 0, v[176:177]
	s_add_i32 m0, s78, 0xc000
	ds_read_b128 v[200:203], v199
	ds_read_b128 v[204:207], v199 offset:1024
	ds_read_b128 v[208:211], v199 offset:2048
	ds_read_b128 v[212:215], v199 offset:3072
	ds_read_b128 v[216:219], v199 offset:4096
	ds_read_b128 v[220:223], v199 offset:5120
	ds_read_b128 v[224:227], v199 offset:6144
	ds_read_b128 v[228:231], v199 offset:7168
	global_load_lds_dwordx4 v[184:185], off
	v_lshl_add_u64 v[184:185], s[70:71], 0, v[178:179]
	s_add_i32 m0, s78, 0xe000
	s_nop 0
	global_load_lds_dwordx4 v[184:185], off
	s_waitcnt vmcnt(8)
	s_waitcnt lgkmcnt(0)
	s_barrier
	s_setprio 1
	v_mfma_f32_16x16x32_bf16 v[102:105], v[130:133], v[200:203], v[102:105]
	v_mfma_f32_16x16x32_bf16 v[98:101], v[138:141], v[200:203], v[98:101]
	v_mfma_f32_16x16x32_bf16 v[110:113], v[130:133], v[208:211], v[110:113]
	v_mfma_f32_16x16x32_bf16 v[106:109], v[138:141], v[208:211], v[106:109]
	v_mfma_f32_16x16x32_bf16 v[118:121], v[130:133], v[216:219], v[118:121]
	v_mfma_f32_16x16x32_bf16 v[114:117], v[138:141], v[216:219], v[114:117]
	v_mfma_f32_16x16x32_bf16 v[126:129], v[130:133], v[224:227], v[126:129]
	v_mfma_f32_16x16x32_bf16 v[122:125], v[138:141], v[224:227], v[122:125]
	v_mfma_f32_16x16x32_bf16 v[102:105], v[134:137], v[204:207], v[102:105]
	v_mfma_f32_16x16x32_bf16 v[98:101], v[142:145], v[204:207], v[98:101]
	v_mfma_f32_16x16x32_bf16 v[110:113], v[134:137], v[212:215], v[110:113]
	v_mfma_f32_16x16x32_bf16 v[106:109], v[142:145], v[212:215], v[106:109]
	v_mfma_f32_16x16x32_bf16 v[118:121], v[134:137], v[220:223], v[118:121]
	v_mfma_f32_16x16x32_bf16 v[114:117], v[142:145], v[220:223], v[114:117]
	v_mfma_f32_16x16x32_bf16 v[126:129], v[134:137], v[228:231], v[126:129]
	v_mfma_f32_16x16x32_bf16 v[122:125], v[142:145], v[228:231], v[122:125]
	v_mfma_f32_16x16x32_bf16 v[38:41], v[146:149], v[200:203], v[38:41]
	v_mfma_f32_16x16x32_bf16 v[34:37], v[154:157], v[200:203], v[34:37]
	v_mfma_f32_16x16x32_bf16 v[46:49], v[146:149], v[208:211], v[46:49]
	v_mfma_f32_16x16x32_bf16 v[42:45], v[154:157], v[208:211], v[42:45]
	v_mfma_f32_16x16x32_bf16 v[54:57], v[146:149], v[216:219], v[54:57]
	v_mfma_f32_16x16x32_bf16 v[50:53], v[154:157], v[216:219], v[50:53]
	v_mfma_f32_16x16x32_bf16 v[62:65], v[146:149], v[224:227], v[62:65]
	v_mfma_f32_16x16x32_bf16 v[58:61], v[154:157], v[224:227], v[58:61]
	v_mfma_f32_16x16x32_bf16 v[38:41], v[150:153], v[204:207], v[38:41]
	v_mfma_f32_16x16x32_bf16 v[34:37], v[158:161], v[204:207], v[34:37]
	v_mfma_f32_16x16x32_bf16 v[46:49], v[150:153], v[212:215], v[46:49]
	v_mfma_f32_16x16x32_bf16 v[42:45], v[158:161], v[212:215], v[42:45]
	s_setprio 3
	s_barrier
	v_mfma_f32_16x16x32_bf16 v[54:57], v[150:153], v[220:223], v[54:57]
	v_mfma_f32_16x16x32_bf16 v[50:53], v[158:161], v[220:223], v[50:53]
	v_mfma_f32_16x16x32_bf16 v[62:65], v[150:153], v[228:231], v[62:65]
	v_mfma_f32_16x16x32_bf16 v[58:61], v[158:161], v[228:231], v[58:61]
	s_setprio 0
	s_add_i32 s96, s90, s77
	v_lshl_add_u64 v[184:185], s[72:73], 0, v[164:165]
	s_mov_b32 m0, s96
	ds_read_b128 v[200:203], v199 offset:16384
	ds_read_b128 v[204:207], v199 offset:17408
	ds_read_b128 v[208:211], v199 offset:18432
	ds_read_b128 v[212:215], v199 offset:19456
	ds_read_b128 v[216:219], v199 offset:20480
	ds_read_b128 v[220:223], v199 offset:21504
	ds_read_b128 v[224:227], v199 offset:22528
	ds_read_b128 v[228:231], v199 offset:23552
	global_load_lds_dwordx4 v[184:185], off
	s_add_i32 m0, s96, 0x2000
	s_add_u32 s96, s72, 0x100000
	v_lshl_add_u64 v[232:233], s[72:73], 0, v[168:169]
	s_addc_u32 s97, s73, 0
	s_add_i32 vcc_lo, s91, s77
	global_load_lds_dwordx4 v[232:233], off
	v_lshl_add_u64 v[234:235], s[96:97], 0, v[164:165]
	s_mov_b32 m0, vcc_lo
	v_lshl_add_u64 v[236:237], s[74:75], 0, v[166:167]
	global_load_lds_dwordx4 v[234:235], off
	v_lshl_add_u64 v[234:235], s[96:97], 0, v[168:169]
	s_add_i32 m0, vcc_lo, 0x2000
	s_nop 0
	global_load_lds_dwordx4 v[234:235], off
	v_lshl_add_u64 v[234:235], s[74:75], 0, v[162:163]
	s_mov_b32 m0, s78
	s_nop 0
	global_load_lds_dwordx4 v[234:235], off
	s_mov_b32 m0, s79
	s_nop 0
	global_load_lds_dwordx4 v[236:237], off
	s_waitcnt vmcnt(8)
	s_waitcnt lgkmcnt(0)
	s_barrier
	s_setprio 1
	v_mfma_f32_16x16x32_bf16 v[70:73], v[130:133], v[200:203], v[70:73]
	v_mfma_f32_16x16x32_bf16 v[66:69], v[138:141], v[200:203], v[66:69]
	v_mfma_f32_16x16x32_bf16 v[78:81], v[130:133], v[208:211], v[78:81]
	v_mfma_f32_16x16x32_bf16 v[74:77], v[138:141], v[208:211], v[74:77]
	v_mfma_f32_16x16x32_bf16 v[86:89], v[130:133], v[216:219], v[86:89]
	v_mfma_f32_16x16x32_bf16 v[82:85], v[138:141], v[216:219], v[82:85]
	v_mfma_f32_16x16x32_bf16 v[94:97], v[130:133], v[224:227], v[94:97]
	v_mfma_f32_16x16x32_bf16 v[90:93], v[138:141], v[224:227], v[90:93]
	v_mfma_f32_16x16x32_bf16 v[70:73], v[134:137], v[204:207], v[70:73]
	v_mfma_f32_16x16x32_bf16 v[66:69], v[142:145], v[204:207], v[66:69]
	v_mfma_f32_16x16x32_bf16 v[78:81], v[134:137], v[212:215], v[78:81]
	v_mfma_f32_16x16x32_bf16 v[74:77], v[142:145], v[212:215], v[74:77]
	v_mfma_f32_16x16x32_bf16 v[86:89], v[134:137], v[220:223], v[86:89]
	v_mfma_f32_16x16x32_bf16 v[82:85], v[142:145], v[220:223], v[82:85]
	v_mfma_f32_16x16x32_bf16 v[94:97], v[134:137], v[228:231], v[94:97]
	v_mfma_f32_16x16x32_bf16 v[90:93], v[142:145], v[228:231], v[90:93]
	v_mfma_f32_16x16x32_bf16 v[6:9], v[146:149], v[200:203], v[6:9]
	v_mfma_f32_16x16x32_bf16 v[2:5], v[154:157], v[200:203], v[2:5]
	v_mfma_f32_16x16x32_bf16 v[14:17], v[146:149], v[208:211], v[14:17]
	v_mfma_f32_16x16x32_bf16 v[10:13], v[154:157], v[208:211], v[10:13]
	v_mfma_f32_16x16x32_bf16 v[22:25], v[146:149], v[216:219], v[22:25]
	v_mfma_f32_16x16x32_bf16 v[18:21], v[154:157], v[216:219], v[18:21]
	v_mfma_f32_16x16x32_bf16 v[30:33], v[146:149], v[224:227], v[30:33]
	v_mfma_f32_16x16x32_bf16 v[26:29], v[154:157], v[224:227], v[26:29]
	v_mfma_f32_16x16x32_bf16 v[6:9], v[150:153], v[204:207], v[6:9]
	v_mfma_f32_16x16x32_bf16 v[2:5], v[158:161], v[204:207], v[2:5]
	v_mfma_f32_16x16x32_bf16 v[14:17], v[150:153], v[212:215], v[14:17]
	v_mfma_f32_16x16x32_bf16 v[10:13], v[158:161], v[212:215], v[10:13]
	s_setprio 3
	s_barrier
	v_mfma_f32_16x16x32_bf16 v[22:25], v[150:153], v[220:223], v[22:25]
	v_mfma_f32_16x16x32_bf16 v[18:21], v[158:161], v[220:223], v[18:21]
	v_mfma_f32_16x16x32_bf16 v[30:33], v[150:153], v[228:231], v[30:33]
	v_mfma_f32_16x16x32_bf16 v[26:29], v[158:161], v[228:231], v[26:29]
	s_setprio 0
	s_add_i32 s96, 0, 0x18000
	s_add_i32 s97, 0, 0x1c000
	v_add_u32_e32 v142, s96, v173
	v_add_u32_e32 v158, s97, v173
	ds_read_b128 v[130:133], v142
	ds_read_b128 v[134:137], v142 offset:1024
	ds_read_b128 v[138:141], v142 offset:2048
	ds_read_b128 v[142:145], v142 offset:3072
	ds_read_b128 v[146:149], v158
	ds_read_b128 v[150:153], v158 offset:1024
	ds_read_b128 v[154:157], v158 offset:2048
	ds_read_b128 v[158:161], v158 offset:3072
	s_add_u32 s74, s74, 0x100000
	s_addc_u32 s75, s75, 0
	s_mov_b32 m0, s80
	v_lshl_add_u64 v[238:239], s[74:75], 0, v[162:163]
	ds_read_b128 v[200:203], v199 offset:32768
	ds_read_b128 v[204:207], v199 offset:33792
	ds_read_b128 v[208:211], v199 offset:34816
	ds_read_b128 v[212:215], v199 offset:35840
	ds_read_b128 v[216:219], v199 offset:36864
	ds_read_b128 v[220:223], v199 offset:37888
	ds_read_b128 v[224:227], v199 offset:38912
	ds_read_b128 v[228:231], v199 offset:39936
	global_load_lds_dwordx4 v[238:239], off
	v_lshl_add_u64 v[238:239], s[74:75], 0, v[166:167]
	s_mov_b32 m0, s81
	s_nop 0
	global_load_lds_dwordx4 v[238:239], off
	s_waitcnt vmcnt(8)
	s_waitcnt lgkmcnt(0)
	s_barrier
	s_setprio 1
	v_mfma_f32_16x16x32_bf16 v[102:105], v[130:133], v[200:203], v[102:105]
	v_mfma_f32_16x16x32_bf16 v[98:101], v[138:141], v[200:203], v[98:101]
	v_mfma_f32_16x16x32_bf16 v[110:113], v[130:133], v[208:211], v[110:113]
	v_mfma_f32_16x16x32_bf16 v[106:109], v[138:141], v[208:211], v[106:109]
	v_mfma_f32_16x16x32_bf16 v[118:121], v[130:133], v[216:219], v[118:121]
	v_mfma_f32_16x16x32_bf16 v[114:117], v[138:141], v[216:219], v[114:117]
	v_mfma_f32_16x16x32_bf16 v[126:129], v[130:133], v[224:227], v[126:129]
	v_mfma_f32_16x16x32_bf16 v[122:125], v[138:141], v[224:227], v[122:125]
	v_mfma_f32_16x16x32_bf16 v[102:105], v[134:137], v[204:207], v[102:105]
	v_mfma_f32_16x16x32_bf16 v[98:101], v[142:145], v[204:207], v[98:101]
	v_mfma_f32_16x16x32_bf16 v[110:113], v[134:137], v[212:215], v[110:113]
	v_mfma_f32_16x16x32_bf16 v[106:109], v[142:145], v[212:215], v[106:109]
	v_mfma_f32_16x16x32_bf16 v[118:121], v[134:137], v[220:223], v[118:121]
	v_mfma_f32_16x16x32_bf16 v[114:117], v[142:145], v[220:223], v[114:117]
	v_mfma_f32_16x16x32_bf16 v[126:129], v[134:137], v[228:231], v[126:129]
	v_mfma_f32_16x16x32_bf16 v[122:125], v[142:145], v[228:231], v[122:125]
	v_mfma_f32_16x16x32_bf16 v[38:41], v[146:149], v[200:203], v[38:41]
	v_mfma_f32_16x16x32_bf16 v[34:37], v[154:157], v[200:203], v[34:37]
	v_mfma_f32_16x16x32_bf16 v[46:49], v[146:149], v[208:211], v[46:49]
	v_mfma_f32_16x16x32_bf16 v[42:45], v[154:157], v[208:211], v[42:45]
	v_mfma_f32_16x16x32_bf16 v[54:57], v[146:149], v[216:219], v[54:57]
	v_mfma_f32_16x16x32_bf16 v[50:53], v[154:157], v[216:219], v[50:53]
	v_mfma_f32_16x16x32_bf16 v[62:65], v[146:149], v[224:227], v[62:65]
	v_mfma_f32_16x16x32_bf16 v[58:61], v[154:157], v[224:227], v[58:61]
	v_mfma_f32_16x16x32_bf16 v[38:41], v[150:153], v[204:207], v[38:41]
	v_mfma_f32_16x16x32_bf16 v[34:37], v[158:161], v[204:207], v[34:37]
	v_mfma_f32_16x16x32_bf16 v[46:49], v[150:153], v[212:215], v[46:49]
	v_mfma_f32_16x16x32_bf16 v[42:45], v[158:161], v[212:215], v[42:45]
	s_setprio 3
	s_barrier
	v_mfma_f32_16x16x32_bf16 v[54:57], v[150:153], v[220:223], v[54:57]
	v_mfma_f32_16x16x32_bf16 v[50:53], v[158:161], v[220:223], v[50:53]
	v_mfma_f32_16x16x32_bf16 v[62:65], v[150:153], v[228:231], v[62:65]
	v_mfma_f32_16x16x32_bf16 v[58:61], v[158:161], v[228:231], v[58:61]
	s_setprio 0
	s_add_i32 s74, s96, s77
	v_lshl_add_u64 v[184:185], v[184:185], 0, s[38:39]
	s_mov_b32 m0, s74
	ds_read_b128 v[200:203], v199 offset:49152
	ds_read_b128 v[204:207], v199 offset:50176
	ds_read_b128 v[208:211], v199 offset:51200
	ds_read_b128 v[212:215], v199 offset:52224
	ds_read_b128 v[216:219], v199 offset:53248
	ds_read_b128 v[220:223], v199 offset:54272
	ds_read_b128 v[224:227], v199 offset:55296
	ds_read_b128 v[228:231], v199 offset:56320
	global_load_lds_dwordx4 v[184:185], off
	s_add_i32 m0, s74, 0x2000
	s_add_u32 s72, s72, 0x100080
	v_lshl_add_u64 v[184:185], v[232:233], 0, s[38:39]
	s_addc_u32 s73, s73, 0
	s_add_i32 s74, s97, s77
	global_load_lds_dwordx4 v[184:185], off
	v_lshl_add_u64 v[184:185], s[72:73], 0, v[164:165]
	s_mov_b32 m0, s74
	s_nop 0
	global_load_lds_dwordx4 v[184:185], off
	v_lshl_add_u64 v[184:185], s[72:73], 0, v[168:169]
	s_add_i32 m0, s74, 0x2000
	s_nop 0
	global_load_lds_dwordx4 v[184:185], off
	v_lshl_add_u64 v[184:185], v[234:235], 0, s[38:39]
	s_mov_b32 m0, s85
	s_nop 0
	global_load_lds_dwordx4 v[184:185], off
	v_lshl_add_u64 v[184:185], v[236:237], 0, s[38:39]
	s_mov_b32 m0, s86
	s_nop 0
	global_load_lds_dwordx4 v[184:185], off
	s_waitcnt vmcnt(8)
	s_waitcnt lgkmcnt(0)
	s_barrier
	s_setprio 1
	v_mfma_f32_16x16x32_bf16 v[70:73], v[130:133], v[200:203], v[70:73]
	v_mfma_f32_16x16x32_bf16 v[66:69], v[138:141], v[200:203], v[66:69]
	v_mfma_f32_16x16x32_bf16 v[78:81], v[130:133], v[208:211], v[78:81]
	v_mfma_f32_16x16x32_bf16 v[74:77], v[138:141], v[208:211], v[74:77]
	v_mfma_f32_16x16x32_bf16 v[86:89], v[130:133], v[216:219], v[86:89]
	v_mfma_f32_16x16x32_bf16 v[82:85], v[138:141], v[216:219], v[82:85]
	v_mfma_f32_16x16x32_bf16 v[94:97], v[130:133], v[224:227], v[94:97]
	v_mfma_f32_16x16x32_bf16 v[90:93], v[138:141], v[224:227], v[90:93]
	v_mfma_f32_16x16x32_bf16 v[70:73], v[134:137], v[204:207], v[70:73]
	v_mfma_f32_16x16x32_bf16 v[66:69], v[142:145], v[204:207], v[66:69]
	v_mfma_f32_16x16x32_bf16 v[78:81], v[134:137], v[212:215], v[78:81]
	v_mfma_f32_16x16x32_bf16 v[74:77], v[142:145], v[212:215], v[74:77]
	v_mfma_f32_16x16x32_bf16 v[86:89], v[134:137], v[220:223], v[86:89]
	v_mfma_f32_16x16x32_bf16 v[82:85], v[142:145], v[220:223], v[82:85]
	v_mfma_f32_16x16x32_bf16 v[94:97], v[134:137], v[228:231], v[94:97]
	v_mfma_f32_16x16x32_bf16 v[90:93], v[142:145], v[228:231], v[90:93]
	v_mfma_f32_16x16x32_bf16 v[6:9], v[146:149], v[200:203], v[6:9]
	v_mfma_f32_16x16x32_bf16 v[2:5], v[154:157], v[200:203], v[2:5]
	v_mfma_f32_16x16x32_bf16 v[14:17], v[146:149], v[208:211], v[14:17]
	v_mfma_f32_16x16x32_bf16 v[10:13], v[154:157], v[208:211], v[10:13]
	v_mfma_f32_16x16x32_bf16 v[22:25], v[146:149], v[216:219], v[22:25]
	v_mfma_f32_16x16x32_bf16 v[18:21], v[154:157], v[216:219], v[18:21]
	v_mfma_f32_16x16x32_bf16 v[30:33], v[146:149], v[224:227], v[30:33]
	v_mfma_f32_16x16x32_bf16 v[26:29], v[154:157], v[224:227], v[26:29]
	v_mfma_f32_16x16x32_bf16 v[6:9], v[150:153], v[204:207], v[6:9]
	v_mfma_f32_16x16x32_bf16 v[2:5], v[158:161], v[204:207], v[2:5]
	v_mfma_f32_16x16x32_bf16 v[14:17], v[150:153], v[212:215], v[14:17]
	v_mfma_f32_16x16x32_bf16 v[10:13], v[158:161], v[212:215], v[10:13]
	s_setprio 3
	s_barrier
	v_mfma_f32_16x16x32_bf16 v[22:25], v[150:153], v[220:223], v[22:25]
	v_mfma_f32_16x16x32_bf16 v[18:21], v[158:161], v[220:223], v[18:21]
	v_mfma_f32_16x16x32_bf16 v[30:33], v[150:153], v[228:231], v[30:33]
	v_mfma_f32_16x16x32_bf16 v[26:29], v[158:161], v[228:231], v[26:29]
	s_setprio 0
	s_add_i32 s95, s95, 2
	s_add_u32 s70, s70, 0x100
	s_addc_u32 s71, s71, 0
	s_add_u32 s93, s93, 0x100
	s_addc_u32 s94, s94, 0
	s_cmp_gt_u32 s95, 61
	s_cbranch_scc0 .LBB0_743
	s_and_b64 vcc, exec, s[40:41]
	s_cbranch_vccz .LBB0_746
	s_barrier

.LBB0_902:
	ds_read_b128 v[144:147], v155
	ds_read_b128 v[148:151], v155 offset:1024
	ds_read_b128 v[158:161], v155 offset:2048
	ds_read_b128 v[162:165], v155 offset:3072
	ds_read_b128 v[166:169], v156
	ds_read_b128 v[170:173], v156 offset:1024
	ds_read_b128 v[174:177], v156 offset:2048
	ds_read_b128 v[178:181], v156 offset:3072
	s_add_u32 s50, s48, 0x100
	s_addc_u32 s51, s49, 0
	s_cmpk_eq_i32 s73, 0xa8
	s_cselect_b32 s55, s9, s51
	s_cselect_b32 s54, s8, s50
	s_cselect_b32 s53, s47, s72
	s_cselect_b32 s52, s46, s71
	v_lshl_add_u64 v[214:215], s[48:49], 0, v[136:137]
	s_add_i32 m0, s57, 0xc000
	ds_read_b128 v[182:185], v157
	ds_read_b128 v[186:189], v157 offset:1024
	ds_read_b128 v[190:193], v157 offset:2048
	ds_read_b128 v[194:197], v157 offset:3072
	ds_read_b128 v[198:201], v157 offset:4096
	ds_read_b128 v[202:205], v157 offset:5120
	ds_read_b128 v[206:209], v157 offset:6144
	ds_read_b128 v[210:213], v157 offset:7168
	global_load_lds_dwordx4 v[214:215], off
	v_lshl_add_u64 v[214:215], s[48:49], 0, v[138:139]
	s_add_i32 m0, s57, 0xe000
	s_nop 0
	global_load_lds_dwordx4 v[214:215], off
	s_waitcnt vmcnt(8)
	s_waitcnt lgkmcnt(0)
	s_barrier
	s_setprio 1
	v_mfma_f32_16x16x32_bf16 v[124:127], v[144:147], v[182:185], v[124:127]
	v_mfma_f32_16x16x32_bf16 v[120:123], v[158:161], v[182:185], v[120:123]
	v_mfma_f32_16x16x32_bf16 v[116:119], v[144:147], v[190:193], v[116:119]
	v_mfma_f32_16x16x32_bf16 v[112:115], v[158:161], v[190:193], v[112:115]
	v_mfma_f32_16x16x32_bf16 v[92:95], v[144:147], v[198:201], v[92:95]
	v_mfma_f32_16x16x32_bf16 v[88:91], v[158:161], v[198:201], v[88:91]
	v_mfma_f32_16x16x32_bf16 v[76:79], v[144:147], v[206:209], v[76:79]
	v_mfma_f32_16x16x32_bf16 v[72:75], v[158:161], v[206:209], v[72:75]
	v_mfma_f32_16x16x32_bf16 v[124:127], v[148:151], v[186:189], v[124:127]
	v_mfma_f32_16x16x32_bf16 v[120:123], v[162:165], v[186:189], v[120:123]
	v_mfma_f32_16x16x32_bf16 v[116:119], v[148:151], v[194:197], v[116:119]
	v_mfma_f32_16x16x32_bf16 v[112:115], v[162:165], v[194:197], v[112:115]
	v_mfma_f32_16x16x32_bf16 v[92:95], v[148:151], v[202:205], v[92:95]
	v_mfma_f32_16x16x32_bf16 v[88:91], v[162:165], v[202:205], v[88:91]
	v_mfma_f32_16x16x32_bf16 v[76:79], v[148:151], v[210:213], v[76:79]
	v_mfma_f32_16x16x32_bf16 v[72:75], v[162:165], v[210:213], v[72:75]
	v_mfma_f32_16x16x32_bf16 v[108:111], v[166:169], v[182:185], v[108:111]
	v_mfma_f32_16x16x32_bf16 v[104:107], v[174:177], v[182:185], v[104:107]
	v_mfma_f32_16x16x32_bf16 v[100:103], v[166:169], v[190:193], v[100:103]
	v_mfma_f32_16x16x32_bf16 v[96:99], v[174:177], v[190:193], v[96:99]
	v_mfma_f32_16x16x32_bf16 v[84:87], v[166:169], v[198:201], v[84:87]
	v_mfma_f32_16x16x32_bf16 v[80:83], v[174:177], v[198:201], v[80:83]
	v_mfma_f32_16x16x32_bf16 v[68:71], v[166:169], v[206:209], v[68:71]
	v_mfma_f32_16x16x32_bf16 v[64:67], v[174:177], v[206:209], v[64:67]
	v_mfma_f32_16x16x32_bf16 v[108:111], v[170:173], v[186:189], v[108:111]
	v_mfma_f32_16x16x32_bf16 v[104:107], v[178:181], v[186:189], v[104:107]
	v_mfma_f32_16x16x32_bf16 v[100:103], v[170:173], v[194:197], v[100:103]
	v_mfma_f32_16x16x32_bf16 v[96:99], v[178:181], v[194:197], v[96:99]
	s_setprio 3
	s_barrier
	v_mfma_f32_16x16x32_bf16 v[84:87], v[170:173], v[202:205], v[84:87]
	v_mfma_f32_16x16x32_bf16 v[80:83], v[178:181], v[202:205], v[80:83]
	v_mfma_f32_16x16x32_bf16 v[68:71], v[170:173], v[210:213], v[68:71]
	v_mfma_f32_16x16x32_bf16 v[64:67], v[178:181], v[210:213], v[64:67]
	s_setprio 0
	s_add_i32 s48, s65, s56
	v_lshl_add_u64 v[214:215], s[52:53], 0, v[130:131]
	s_mov_b32 m0, s48
	ds_read_b128 v[182:185], v157 offset:16384
	ds_read_b128 v[186:189], v157 offset:17408
	ds_read_b128 v[190:193], v157 offset:18432
	ds_read_b128 v[194:197], v157 offset:19456
	ds_read_b128 v[198:201], v157 offset:20480
	ds_read_b128 v[202:205], v157 offset:21504
	ds_read_b128 v[206:209], v157 offset:22528
	ds_read_b128 v[210:213], v157 offset:23552
	global_load_lds_dwordx4 v[214:215], off
	s_add_i32 m0, s48, 0x2000
	s_add_u32 s48, s52, 0x2b0000
	v_lshl_add_u64 v[216:217], s[52:53], 0, v[134:135]
	s_addc_u32 s49, s53, 0
	s_add_i32 s74, s66, s56
	global_load_lds_dwordx4 v[216:217], off
	v_lshl_add_u64 v[218:219], s[48:49], 0, v[130:131]
	s_mov_b32 m0, s74
	v_lshl_add_u64 v[220:221], s[54:55], 0, v[132:133]
	global_load_lds_dwordx4 v[218:219], off
	v_lshl_add_u64 v[218:219], s[48:49], 0, v[134:135]
	s_add_i32 m0, s74, 0x2000
	s_nop 0
	global_load_lds_dwordx4 v[218:219], off
	v_lshl_add_u64 v[218:219], s[54:55], 0, v[128:129]
	s_mov_b32 m0, s57
	s_nop 0
	global_load_lds_dwordx4 v[218:219], off
	s_mov_b32 m0, s58
	s_nop 0
	global_load_lds_dwordx4 v[220:221], off
	s_waitcnt vmcnt(8)
	s_waitcnt lgkmcnt(0)
	s_barrier
	s_setprio 1
	v_mfma_f32_16x16x32_bf16 v[60:63], v[144:147], v[182:185], v[60:63]
	v_mfma_f32_16x16x32_bf16 v[56:59], v[158:161], v[182:185], v[56:59]
	v_mfma_f32_16x16x32_bf16 v[44:47], v[144:147], v[190:193], v[44:47]
	v_mfma_f32_16x16x32_bf16 v[40:43], v[158:161], v[190:193], v[40:43]
	v_mfma_f32_16x16x32_bf16 v[28:31], v[144:147], v[198:201], v[28:31]
	v_mfma_f32_16x16x32_bf16 v[24:27], v[158:161], v[198:201], v[24:27]
	v_mfma_f32_16x16x32_bf16 v[12:15], v[144:147], v[206:209], v[12:15]
	v_mfma_f32_16x16x32_bf16 v[8:11], v[158:161], v[206:209], v[8:11]
	v_mfma_f32_16x16x32_bf16 v[60:63], v[148:151], v[186:189], v[60:63]
	v_mfma_f32_16x16x32_bf16 v[56:59], v[162:165], v[186:189], v[56:59]
	v_mfma_f32_16x16x32_bf16 v[44:47], v[148:151], v[194:197], v[44:47]
	v_mfma_f32_16x16x32_bf16 v[40:43], v[162:165], v[194:197], v[40:43]
	v_mfma_f32_16x16x32_bf16 v[28:31], v[148:151], v[202:205], v[28:31]
	v_mfma_f32_16x16x32_bf16 v[24:27], v[162:165], v[202:205], v[24:27]
	v_mfma_f32_16x16x32_bf16 v[12:15], v[148:151], v[210:213], v[12:15]
	v_mfma_f32_16x16x32_bf16 v[8:11], v[162:165], v[210:213], v[8:11]
	v_mfma_f32_16x16x32_bf16 v[52:55], v[166:169], v[182:185], v[52:55]
	v_mfma_f32_16x16x32_bf16 v[48:51], v[174:177], v[182:185], v[48:51]
	v_mfma_f32_16x16x32_bf16 v[36:39], v[166:169], v[190:193], v[36:39]
	v_mfma_f32_16x16x32_bf16 v[32:35], v[174:177], v[190:193], v[32:35]
	v_mfma_f32_16x16x32_bf16 v[20:23], v[166:169], v[198:201], v[20:23]
	v_mfma_f32_16x16x32_bf16 v[16:19], v[174:177], v[198:201], v[16:19]
	v_mfma_f32_16x16x32_bf16 v[4:7], v[166:169], v[206:209], v[4:7]
	v_mfma_f32_16x16x32_bf16 v[0:3], v[174:177], v[206:209], v[0:3]
	v_mfma_f32_16x16x32_bf16 v[52:55], v[170:173], v[186:189], v[52:55]
	v_mfma_f32_16x16x32_bf16 v[48:51], v[178:181], v[186:189], v[48:51]
	v_mfma_f32_16x16x32_bf16 v[36:39], v[170:173], v[194:197], v[36:39]
	v_mfma_f32_16x16x32_bf16 v[32:35], v[178:181], v[194:197], v[32:35]
	s_setprio 3
	s_barrier
	v_mfma_f32_16x16x32_bf16 v[20:23], v[170:173], v[202:205], v[20:23]
	v_mfma_f32_16x16x32_bf16 v[16:19], v[178:181], v[202:205], v[16:19]
	v_mfma_f32_16x16x32_bf16 v[4:7], v[170:173], v[210:213], v[4:7]
	v_mfma_f32_16x16x32_bf16 v[0:3], v[178:181], v[210:213], v[0:3]
	s_setprio 0
	s_add_i32 s74, 0, 0x18000
	s_add_i32 s75, 0, 0x1c000
	v_add_u32_e32 v162, s74, v153
	v_add_u32_e32 v178, s75, v153
	ds_read_b128 v[144:147], v162
	ds_read_b128 v[148:151], v162 offset:1024
	ds_read_b128 v[158:161], v162 offset:2048
	ds_read_b128 v[162:165], v162 offset:3072
	ds_read_b128 v[166:169], v178
	ds_read_b128 v[170:173], v178 offset:1024
	ds_read_b128 v[174:177], v178 offset:2048
	ds_read_b128 v[178:181], v178 offset:3072
	s_add_u32 s48, s54, 0x2b0000
	s_addc_u32 s49, s55, 0
	s_mov_b32 m0, s59
	v_lshl_add_u64 v[222:223], s[48:49], 0, v[128:129]
	ds_read_b128 v[182:185], v157 offset:32768
	ds_read_b128 v[186:189], v157 offset:33792
	ds_read_b128 v[190:193], v157 offset:34816
	ds_read_b128 v[194:197], v157 offset:35840
	ds_read_b128 v[198:201], v157 offset:36864
	ds_read_b128 v[202:205], v157 offset:37888
	ds_read_b128 v[206:209], v157 offset:38912
	ds_read_b128 v[210:213], v157 offset:39936
	global_load_lds_dwordx4 v[222:223], off
	v_lshl_add_u64 v[222:223], s[48:49], 0, v[132:133]
	s_mov_b32 m0, s60
	s_nop 0
	global_load_lds_dwordx4 v[222:223], off
	s_waitcnt vmcnt(8)
	s_waitcnt lgkmcnt(0)
	s_barrier
	s_setprio 1
	v_mfma_f32_16x16x32_bf16 v[124:127], v[144:147], v[182:185], v[124:127]
	v_mfma_f32_16x16x32_bf16 v[120:123], v[158:161], v[182:185], v[120:123]
	v_mfma_f32_16x16x32_bf16 v[116:119], v[144:147], v[190:193], v[116:119]
	v_mfma_f32_16x16x32_bf16 v[112:115], v[158:161], v[190:193], v[112:115]
	v_mfma_f32_16x16x32_bf16 v[92:95], v[144:147], v[198:201], v[92:95]
	v_mfma_f32_16x16x32_bf16 v[88:91], v[158:161], v[198:201], v[88:91]
	v_mfma_f32_16x16x32_bf16 v[76:79], v[144:147], v[206:209], v[76:79]
	v_mfma_f32_16x16x32_bf16 v[72:75], v[158:161], v[206:209], v[72:75]
	v_mfma_f32_16x16x32_bf16 v[124:127], v[148:151], v[186:189], v[124:127]
	v_mfma_f32_16x16x32_bf16 v[120:123], v[162:165], v[186:189], v[120:123]
	v_mfma_f32_16x16x32_bf16 v[116:119], v[148:151], v[194:197], v[116:119]
	v_mfma_f32_16x16x32_bf16 v[112:115], v[162:165], v[194:197], v[112:115]
	v_mfma_f32_16x16x32_bf16 v[92:95], v[148:151], v[202:205], v[92:95]
	v_mfma_f32_16x16x32_bf16 v[88:91], v[162:165], v[202:205], v[88:91]
	v_mfma_f32_16x16x32_bf16 v[76:79], v[148:151], v[210:213], v[76:79]
	v_mfma_f32_16x16x32_bf16 v[72:75], v[162:165], v[210:213], v[72:75]
	v_mfma_f32_16x16x32_bf16 v[108:111], v[166:169], v[182:185], v[108:111]
	v_mfma_f32_16x16x32_bf16 v[104:107], v[174:177], v[182:185], v[104:107]
	v_mfma_f32_16x16x32_bf16 v[100:103], v[166:169], v[190:193], v[100:103]
	v_mfma_f32_16x16x32_bf16 v[96:99], v[174:177], v[190:193], v[96:99]
	v_mfma_f32_16x16x32_bf16 v[84:87], v[166:169], v[198:201], v[84:87]
	v_mfma_f32_16x16x32_bf16 v[80:83], v[174:177], v[198:201], v[80:83]
	v_mfma_f32_16x16x32_bf16 v[68:71], v[166:169], v[206:209], v[68:71]
	v_mfma_f32_16x16x32_bf16 v[64:67], v[174:177], v[206:209], v[64:67]
	v_mfma_f32_16x16x32_bf16 v[108:111], v[170:173], v[186:189], v[108:111]
	v_mfma_f32_16x16x32_bf16 v[104:107], v[178:181], v[186:189], v[104:107]
	v_mfma_f32_16x16x32_bf16 v[100:103], v[170:173], v[194:197], v[100:103]
	v_mfma_f32_16x16x32_bf16 v[96:99], v[178:181], v[194:197], v[96:99]
	s_setprio 3
	s_barrier
	v_mfma_f32_16x16x32_bf16 v[84:87], v[170:173], v[202:205], v[84:87]
	v_mfma_f32_16x16x32_bf16 v[80:83], v[178:181], v[202:205], v[80:83]
	v_mfma_f32_16x16x32_bf16 v[68:71], v[170:173], v[210:213], v[68:71]
	v_mfma_f32_16x16x32_bf16 v[64:67], v[178:181], v[210:213], v[64:67]
	s_setprio 0
	s_add_i32 s48, s74, s56
	v_lshl_add_u64 v[214:215], v[214:215], 0, s[30:31]
	s_mov_b32 m0, s48
	ds_read_b128 v[182:185], v157 offset:49152
	ds_read_b128 v[186:189], v157 offset:50176
	ds_read_b128 v[190:193], v157 offset:51200
	ds_read_b128 v[194:197], v157 offset:52224
	ds_read_b128 v[198:201], v157 offset:53248
	ds_read_b128 v[202:205], v157 offset:54272
	ds_read_b128 v[206:209], v157 offset:55296
	ds_read_b128 v[210:213], v157 offset:56320
	global_load_lds_dwordx4 v[214:215], off
	s_add_i32 m0, s48, 0x2000
	s_add_u32 s48, s52, 0x2b0080
	v_lshl_add_u64 v[214:215], v[216:217], 0, s[30:31]
	s_addc_u32 s49, s53, 0
	s_add_i32 s52, s75, s56
	global_load_lds_dwordx4 v[214:215], off
	v_lshl_add_u64 v[214:215], s[48:49], 0, v[130:131]
	s_mov_b32 m0, s52
	s_nop 0
	global_load_lds_dwordx4 v[214:215], off
	v_lshl_add_u64 v[214:215], s[48:49], 0, v[134:135]
	s_add_i32 m0, s52, 0x2000
	s_nop 0
	global_load_lds_dwordx4 v[214:215], off
	v_lshl_add_u64 v[214:215], v[218:219], 0, s[30:31]
	s_mov_b32 m0, s62
	s_nop 0
	global_load_lds_dwordx4 v[214:215], off
	v_lshl_add_u64 v[214:215], v[220:221], 0, s[30:31]
	s_mov_b32 m0, s63
	s_nop 0
	global_load_lds_dwordx4 v[214:215], off
	s_waitcnt vmcnt(8)
	s_waitcnt lgkmcnt(0)
	s_barrier
	s_setprio 1
	v_mfma_f32_16x16x32_bf16 v[60:63], v[144:147], v[182:185], v[60:63]
	v_mfma_f32_16x16x32_bf16 v[56:59], v[158:161], v[182:185], v[56:59]
	v_mfma_f32_16x16x32_bf16 v[44:47], v[144:147], v[190:193], v[44:47]
	v_mfma_f32_16x16x32_bf16 v[40:43], v[158:161], v[190:193], v[40:43]
	v_mfma_f32_16x16x32_bf16 v[28:31], v[144:147], v[198:201], v[28:31]
	v_mfma_f32_16x16x32_bf16 v[24:27], v[158:161], v[198:201], v[24:27]
	v_mfma_f32_16x16x32_bf16 v[12:15], v[144:147], v[206:209], v[12:15]
	v_mfma_f32_16x16x32_bf16 v[8:11], v[158:161], v[206:209], v[8:11]
	v_mfma_f32_16x16x32_bf16 v[60:63], v[148:151], v[186:189], v[60:63]
	v_mfma_f32_16x16x32_bf16 v[56:59], v[162:165], v[186:189], v[56:59]
	v_mfma_f32_16x16x32_bf16 v[44:47], v[148:151], v[194:197], v[44:47]
	v_mfma_f32_16x16x32_bf16 v[40:43], v[162:165], v[194:197], v[40:43]
	v_mfma_f32_16x16x32_bf16 v[28:31], v[148:151], v[202:205], v[28:31]
	v_mfma_f32_16x16x32_bf16 v[24:27], v[162:165], v[202:205], v[24:27]
	v_mfma_f32_16x16x32_bf16 v[12:15], v[148:151], v[210:213], v[12:15]
	v_mfma_f32_16x16x32_bf16 v[8:11], v[162:165], v[210:213], v[8:11]
	v_mfma_f32_16x16x32_bf16 v[52:55], v[166:169], v[182:185], v[52:55]
	v_mfma_f32_16x16x32_bf16 v[48:51], v[174:177], v[182:185], v[48:51]
	v_mfma_f32_16x16x32_bf16 v[36:39], v[166:169], v[190:193], v[36:39]
	v_mfma_f32_16x16x32_bf16 v[32:35], v[174:177], v[190:193], v[32:35]
	v_mfma_f32_16x16x32_bf16 v[20:23], v[166:169], v[198:201], v[20:23]
	v_mfma_f32_16x16x32_bf16 v[16:19], v[174:177], v[198:201], v[16:19]
	v_mfma_f32_16x16x32_bf16 v[4:7], v[166:169], v[206:209], v[4:7]
	v_mfma_f32_16x16x32_bf16 v[0:3], v[174:177], v[206:209], v[0:3]
	v_mfma_f32_16x16x32_bf16 v[52:55], v[170:173], v[186:189], v[52:55]
	v_mfma_f32_16x16x32_bf16 v[48:51], v[178:181], v[186:189], v[48:51]
	v_mfma_f32_16x16x32_bf16 v[36:39], v[170:173], v[194:197], v[36:39]
	v_mfma_f32_16x16x32_bf16 v[32:35], v[178:181], v[194:197], v[32:35]
	s_setprio 3
	s_barrier
	v_mfma_f32_16x16x32_bf16 v[20:23], v[170:173], v[202:205], v[20:23]
	v_mfma_f32_16x16x32_bf16 v[16:19], v[178:181], v[202:205], v[16:19]
	v_mfma_f32_16x16x32_bf16 v[4:7], v[170:173], v[210:213], v[4:7]
	v_mfma_f32_16x16x32_bf16 v[0:3], v[178:181], v[210:213], v[0:3]
	s_setprio 0
	s_add_i32 s73, s73, 2
	s_add_u32 s71, s71, 0x100
	s_addc_u32 s72, s72, 0
	s_cmpk_gt_u32 s73, 0xa9
	s_mov_b64 s[48:49], s[50:51]
	s_cbranch_scc0 .LBB0_902
	s_and_b64 vcc, exec, s[34:35]
	s_cbranch_vccz .LBB0_905
	s_barrier
